# E10 + mixers A/B/D output stores widened to dwordx4 via v_permlane32_swap between lane halves (4 stores instead of 8 per 32-query tile), counted waits re-derived
# baseline (speedup 1.0000x reference)
; __device__ __forceinline__ unsigned cvt_pk_bf16(float lo, float hi) { f32x2_c v = {lo, hi}; bf16x2_c b = __builtin_convertvector(v, bf16x2_c); return __builtin_bit_cast(unsigned, b); }
; __device__ __forceinline__ float silu_f(float z) { return z * __builtin_amdgcn_rcpf(1.f + __expf(-z)); }
; __device__ __forceinline__ void la_store(const LA& st, bool use_sink, float sink2, const u32x2 (&zv)[8], bf16_t* yrow, int hi) {
;     float l = st.l; { auto rr = __builtin_amdgcn_permlane32_swap(__float_as_uint(l), __float_as_uint(l), false, false); l = __uint_as_float(rr[0]) + __uint_as_float(rr[1]); }
;     float inv;
;     if (use_sink) { const float m2 = fmaxf(st.m, sink2), a = __builtin_amdgcn_exp2f(st.m - m2); inv = a * __builtin_amdgcn_rcpf(l * a + __builtin_amdgcn_exp2f(sink2 - m2)); }
;     else inv = __builtin_amdgcn_rcpf(l);
; #pragma unroll
;     for (int db = 0; db < 2; ++db)
; #pragma unroll
;         for (int g = 0; g < 4; ++g) { const int c = 32 * db + 8 * g + 4 * hi; const u32x2 z = zv[4 * db + g];
;             const f32x16& o = db ? st.o1 : st.o0;
;             u32x2 w; w.x = cvt_pk_bf16(o[4 * g] * inv * silu_f(bf_lo(z.x)), o[4 * g + 1] * inv * silu_f(bf_hi(z.x)));
;             w.y = cvt_pk_bf16(o[4 * g + 2] * inv * silu_f(bf_lo(z.y)), o[4 * g + 3] * inv * silu_f(bf_hi(z.y)));
;             *(u32x2*)(yrow + c) = w; }
; __global__ void __launch_bounds__(NWAVES * 64, 2) mk_fwd(Args args) {
;     ...
;                 const float sk2 = attn_sink[l * 8 + h] * LOG2E;
;                 la_store(sa, true, sk2, za, Yb + (size_t)tqa * DMODEL + h * 64, hi);
;                 la_store(sb, true, sk2, zb, Yb + (size_t)tqb * DMODEL + h * 64, hi);
.LBB0_677:
	s_add_u32 s56, s34, 0x1aa00000
	s_addc_u32 s57, s35, 0
	s_add_u32 s42, s34, 0x1ce00000
	s_addc_u32 s43, s35, 0
	s_ashr_i32 s37, s36, 31
	s_lshl_b64 s[6:7], s[36:37], 2
	s_add_u32 s6, s28, s6
	s_addc_u32 s7, s29, s7
	global_load_dword v65, v189, s[6:7]
	v_max_f32_e32 v67, v196, v196
	s_mov_b32 s6, 0x3fb8aa3b
	v_mov_b32_e32 v64, v193
	s_nop 1
	v_permlane32_swap_b32_e32 v193, v64
	v_add_f32_e32 v64, v193, v64
	v_and_b32_e32 v71, 0xffff0000, v144
	v_lshlrev_b64 v[68:69], 12, v[182:183]
	v_lshl_add_u64 v[68:69], s[42:43], 0, v[68:69]
	v_lshl_add_u64 v[68:69], v[68:69], 0, s[70:71]
	s_bfe_u32 s54, s58, 0x10006
	s_lshl_b32 s55, s54, 5
	s_movk_i32 s22, 0xffef
	s_lshl_b32 s0, s0, 10
	s_mov_b32 s60, 0
	s_waitcnt vmcnt(0)
	v_mul_f32_e32 v66, 0x3fb8aa3b, v65
	v_max_f32_e32 v67, v67, v66
	v_sub_f32_e32 v70, v196, v67
	v_fma_f32 v67, v65, s6, -v67
	v_exp_f32_e32 v70, v70
	v_exp_f32_e32 v67, v67
	s_nop 0
	v_fmac_f32_e32 v67, v64, v70
	v_rcp_f32_e32 v64, v67
	s_nop 0
	v_mul_f32_e32 v64, v70, v64
	v_lshlrev_b32_e32 v70, 16, v144
	v_mul_f32_e32 v67, 0xbfb8aa3b, v70
	v_exp_f32_e32 v67, v67
	v_pk_mul_f32 v[48:49], v[48:49], v[64:65] op_sel_hi:[1,0]
	v_pk_mul_f32 v[50:51], v[50:51], v[64:65] op_sel_hi:[1,0]
	v_lshlrev_b32_e32 v144, 1, v180
	v_add_f32_e32 v67, 1.0, v67
	v_rcp_f32_e32 v72, v67
	v_mul_f32_e32 v67, 0xbfb8aa3b, v71
	v_exp_f32_e32 v67, v67
	v_pk_mul_f32 v[52:53], v[52:53], v[64:65] op_sel_hi:[1,0]
	v_pk_mul_f32 v[54:55], v[54:55], v[64:65] op_sel_hi:[1,0]
	v_pk_mul_f32 v[32:33], v[32:33], v[64:65] op_sel_hi:[1,0]
	v_add_f32_e32 v67, 1.0, v67
	v_rcp_f32_e32 v73, v67
	v_pk_mul_f32 v[34:35], v[34:35], v[64:65] op_sel_hi:[1,0]
	v_pk_mul_f32 v[36:37], v[36:37], v[64:65] op_sel_hi:[1,0]
	v_pk_mul_f32 v[38:39], v[38:39], v[64:65] op_sel_hi:[1,0]
	v_pk_mul_f32 v[70:71], v[72:73], v[70:71]
	s_nop 0
	v_pk_mul_f32 v[48:49], v[70:71], v[48:49]
	s_nop 0
	v_cvt_pk_bf16_f32 v70, v48, v49
	v_lshlrev_b32_e32 v48, 16, v145
	v_mul_f32_e32 v67, 0xbfb8aa3b, v48
	v_exp_f32_e32 v67, v67
	v_and_b32_e32 v49, 0xffff0000, v145
	v_mov_b32_e32 v145, v189
	v_add_f32_e32 v67, 1.0, v67
	v_rcp_f32_e32 v72, v67
	v_mul_f32_e32 v67, 0xbfb8aa3b, v49
	v_exp_f32_e32 v67, v67
	s_nop 0
	v_add_f32_e32 v67, 1.0, v67
	v_rcp_f32_e32 v73, v67
	s_nop 0
	v_pk_mul_f32 v[48:49], v[72:73], v[48:49]
	s_nop 0
	v_pk_mul_f32 v[48:49], v[48:49], v[50:51]
	v_lshlrev_b32_e32 v50, 16, v178
	v_mul_f32_e32 v67, 0xbfb8aa3b, v50
	v_exp_f32_e32 v67, v67
	v_and_b32_e32 v51, 0xffff0000, v178
	v_cvt_pk_bf16_f32 v71, v48, v49
	v_lshl_add_u64 v[48:49], v[68:69], 0, v[144:145]
	v_add_f32_e32 v67, 1.0, v67
	v_rcp_f32_e32 v68, v67
	v_mul_f32_e32 v67, 0xbfb8aa3b, v51
	v_exp_f32_e32 v67, v67
	v_lshrrev_b32_e32 v236, 2, v252
	v_and_b32_e32 v236, 8, v236
	v_add_u32_e32 v234, v48, v236
	v_mov_b32_e32 v235, v49
	v_mov_b32_e32 v228, v70
	v_mov_b32_e32 v229, v71
	v_add_f32_e32 v67, 1.0, v67
	v_rcp_f32_e32 v69, v67
	s_nop 0
	v_pk_mul_f32 v[50:51], v[68:69], v[50:51]
	s_nop 0
	v_pk_mul_f32 v[50:51], v[50:51], v[52:53]
	v_lshlrev_b32_e32 v52, 16, v179
	v_cvt_pk_bf16_f32 v50, v50, v51
	v_mul_f32_e32 v51, 0xbfb8aa3b, v52
	v_exp_f32_e32 v51, v51
	v_and_b32_e32 v53, 0xffff0000, v179
	v_add_f32_e32 v51, 1.0, v51
	v_rcp_f32_e32 v68, v51
	v_mul_f32_e32 v51, 0xbfb8aa3b, v53
	v_exp_f32_e32 v51, v51
	s_nop 0
	v_add_f32_e32 v51, 1.0, v51
	v_rcp_f32_e32 v69, v51
	s_nop 0
	v_pk_mul_f32 v[52:53], v[68:69], v[52:53]
	s_nop 0
	v_pk_mul_f32 v[52:53], v[52:53], v[54:55]
	v_pk_mul_f32 v[54:55], v[56:57], v[64:65] op_sel_hi:[1,0]
	v_cvt_pk_bf16_f32 v51, v52, v53
	v_mov_b32_e32 v230, v50
	v_mov_b32_e32 v231, v51
	s_nop 1
	v_permlane32_swap_b32_e32 v228, v230
	v_permlane32_swap_b32_e32 v229, v231
	global_store_dwordx4 v[234:235], v[228:231], off
	v_lshlrev_b32_e32 v50, 16, v176
	v_and_b32_e32 v51, 0xffff0000, v176
	v_mul_f32_e32 v52, 0xbfb8aa3b, v50
	v_mul_f32_e32 v53, 0xbfb8aa3b, v51
	v_exp_f32_e32 v52, v52
	v_exp_f32_e32 v53, v53
	v_add_f32_e32 v52, 1.0, v52
	v_add_f32_e32 v53, 1.0, v53
	v_rcp_f32_e32 v52, v52
	v_rcp_f32_e32 v53, v53
	s_nop 0
	v_pk_mul_f32 v[50:51], v[52:53], v[50:51]
	s_nop 0
	v_pk_mul_f32 v[50:51], v[50:51], v[54:55]
	v_lshlrev_b32_e32 v52, 16, v177
	v_cvt_pk_bf16_f32 v50, v50, v51
	v_mul_f32_e32 v51, 0xbfb8aa3b, v52
	v_exp_f32_e32 v51, v51
	v_and_b32_e32 v53, 0xffff0000, v177
	v_pk_mul_f32 v[54:55], v[58:59], v[64:65] op_sel_hi:[1,0]
	v_add_f32_e32 v51, 1.0, v51
	v_rcp_f32_e32 v56, v51
	v_mul_f32_e32 v51, 0xbfb8aa3b, v53
	v_exp_f32_e32 v51, v51
	s_nop 0
	v_add_f32_e32 v51, 1.0, v51
	v_rcp_f32_e32 v57, v51
	s_nop 0
	v_pk_mul_f32 v[52:53], v[56:57], v[52:53]
	s_nop 0
	v_pk_mul_f32 v[52:53], v[52:53], v[54:55]
	v_pk_mul_f32 v[54:55], v[60:61], v[64:65] op_sel_hi:[1,0]
	v_cvt_pk_bf16_f32 v51, v52, v53
	v_mov_b32_e32 v228, v50
	v_mov_b32_e32 v229, v51
	v_lshlrev_b32_e32 v50, 16, v174
	v_and_b32_e32 v51, 0xffff0000, v174
	v_mul_f32_e32 v52, 0xbfb8aa3b, v50
	v_mul_f32_e32 v53, 0xbfb8aa3b, v51
	v_exp_f32_e32 v52, v52
	v_exp_f32_e32 v53, v53
	v_pk_mul_f32 v[56:57], v[62:63], v[64:65] op_sel_hi:[1,0]
	v_add_f32_e32 v52, 1.0, v52
	v_add_f32_e32 v53, 1.0, v53
	v_rcp_f32_e32 v52, v52
	v_rcp_f32_e32 v53, v53
	s_nop 0
	v_pk_mul_f32 v[50:51], v[52:53], v[50:51]
	s_nop 0
	v_pk_mul_f32 v[50:51], v[50:51], v[54:55]
	v_lshlrev_b32_e32 v52, 16, v175
	v_cvt_pk_bf16_f32 v50, v50, v51
	v_mul_f32_e32 v51, 0xbfb8aa3b, v52
	v_exp_f32_e32 v51, v51
	v_and_b32_e32 v53, 0xffff0000, v175
	v_add_f32_e32 v51, 1.0, v51
	v_rcp_f32_e32 v54, v51
	v_mul_f32_e32 v51, 0xbfb8aa3b, v53
	v_exp_f32_e32 v51, v51
	s_nop 0
	v_add_f32_e32 v51, 1.0, v51
	v_rcp_f32_e32 v55, v51
	s_nop 0
	v_pk_mul_f32 v[52:53], v[54:55], v[52:53]
	s_nop 0
	v_pk_mul_f32 v[52:53], v[52:53], v[56:57]
; __device__ __forceinline__ unsigned cvt_pk_bf16(float lo, float hi) { f32x2_c v = {lo, hi}; bf16x2_c b = __builtin_convertvector(v, bf16x2_c); return __builtin_bit_cast(unsigned, b); }
; __device__ __forceinline__ float silu_f(float z) { return z * __builtin_amdgcn_rcpf(1.f + __expf(-z)); }
; __device__ __forceinline__ void la_store(const LA& st, bool use_sink, float sink2, const u32x2 (&zv)[8], bf16_t* yrow, int hi) {
;     float l = st.l; { auto rr = __builtin_amdgcn_permlane32_swap(__float_as_uint(l), __float_as_uint(l), false, false); l = __uint_as_float(rr[0]) + __uint_as_float(rr[1]); }
;     float inv;
;     if (use_sink) { const float m2 = fmaxf(st.m, sink2), a = __builtin_amdgcn_exp2f(st.m - m2); inv = a * __builtin_amdgcn_rcpf(l * a + __builtin_amdgcn_exp2f(sink2 - m2)); }
;     else inv = __builtin_amdgcn_rcpf(l);
; #pragma unroll
;     for (int db = 0; db < 2; ++db)
; #pragma unroll
;         for (int g = 0; g < 4; ++g) { const int c = 32 * db + 8 * g + 4 * hi; const u32x2 z = zv[4 * db + g];
;             const f32x16& o = db ? st.o1 : st.o0;
;             u32x2 w; w.x = cvt_pk_bf16(o[4 * g] * inv * silu_f(bf_lo(z.x)), o[4 * g + 1] * inv * silu_f(bf_hi(z.x)));
;             w.y = cvt_pk_bf16(o[4 * g + 2] * inv * silu_f(bf_lo(z.y)), o[4 * g + 3] * inv * silu_f(bf_hi(z.y)));
;             *(u32x2*)(yrow + c) = w; }
; __global__ void __launch_bounds__(NWAVES * 64, 2) mk_fwd(Args args) {
;     ...
;                 const float sk2 = attn_sink[l * 8 + h] * LOG2E;
;                 la_store(sa, true, sk2, za, Yb + (size_t)tqa * DMODEL + h * 64, hi);
;                 la_store(sb, true, sk2, zb, Yb + (size_t)tqb * DMODEL + h * 64, hi);
	s_nop 0
	v_cvt_pk_bf16_f32 v51, v52, v53
	v_mov_b32_e32 v230, v50
	v_mov_b32_e32 v231, v51
	s_nop 1
	v_permlane32_swap_b32_e32 v228, v230
	v_permlane32_swap_b32_e32 v229, v231
	global_store_dwordx4 v[234:235], v[228:231], off offset:32
	v_lshlrev_b32_e32 v50, 16, v172
	v_and_b32_e32 v51, 0xffff0000, v172
	v_mul_f32_e32 v52, 0xbfb8aa3b, v50
	v_mul_f32_e32 v53, 0xbfb8aa3b, v51
	v_exp_f32_e32 v52, v52
	v_exp_f32_e32 v53, v53
	v_add_f32_e32 v52, 1.0, v52
	v_add_f32_e32 v53, 1.0, v53
	v_rcp_f32_e32 v52, v52
	v_rcp_f32_e32 v53, v53
	s_nop 0
	v_pk_mul_f32 v[50:51], v[52:53], v[50:51]
	s_nop 0
	v_pk_mul_f32 v[32:33], v[50:51], v[32:33]
	v_lshlrev_b32_e32 v50, 16, v173
	v_cvt_pk_bf16_f32 v32, v32, v33
	v_mul_f32_e32 v33, 0xbfb8aa3b, v50
	v_exp_f32_e32 v33, v33
	v_and_b32_e32 v51, 0xffff0000, v173
	v_add_f32_e32 v33, 1.0, v33
	v_rcp_f32_e32 v52, v33
	v_mul_f32_e32 v33, 0xbfb8aa3b, v51
	v_exp_f32_e32 v33, v33
	s_nop 0
	v_add_f32_e32 v33, 1.0, v33
	v_rcp_f32_e32 v53, v33
	s_nop 0
	v_pk_mul_f32 v[50:51], v[52:53], v[50:51]
	s_nop 0
	v_pk_mul_f32 v[34:35], v[50:51], v[34:35]
	s_nop 0
	v_cvt_pk_bf16_f32 v33, v34, v35
	v_mov_b32_e32 v228, v32
	v_mov_b32_e32 v229, v33
	v_lshlrev_b32_e32 v32, 16, v170
	v_and_b32_e32 v33, 0xffff0000, v170
	v_mul_f32_e32 v34, 0xbfb8aa3b, v32
	v_mul_f32_e32 v35, 0xbfb8aa3b, v33
	v_exp_f32_e32 v34, v34
	v_exp_f32_e32 v35, v35
	v_add_f32_e32 v34, 1.0, v34
	v_add_f32_e32 v35, 1.0, v35
	v_rcp_f32_e32 v34, v34
	v_rcp_f32_e32 v35, v35
	s_nop 0
	v_pk_mul_f32 v[32:33], v[34:35], v[32:33]
	s_nop 0
	v_pk_mul_f32 v[32:33], v[32:33], v[36:37]
	v_lshlrev_b32_e32 v34, 16, v171
	v_cvt_pk_bf16_f32 v32, v32, v33
	v_mul_f32_e32 v33, 0xbfb8aa3b, v34
	v_exp_f32_e32 v33, v33
	v_and_b32_e32 v35, 0xffff0000, v171
	v_add_f32_e32 v33, 1.0, v33
	v_rcp_f32_e32 v36, v33
	v_mul_f32_e32 v33, 0xbfb8aa3b, v35
	v_exp_f32_e32 v33, v33
	s_nop 0
	v_add_f32_e32 v33, 1.0, v33
	v_rcp_f32_e32 v37, v33
	s_nop 0
	v_pk_mul_f32 v[34:35], v[36:37], v[34:35]
	s_nop 0
	v_pk_mul_f32 v[34:35], v[34:35], v[38:39]
	v_pk_mul_f32 v[36:37], v[40:41], v[64:65] op_sel_hi:[1,0]
	v_cvt_pk_bf16_f32 v33, v34, v35
	v_mov_b32_e32 v230, v32
	v_mov_b32_e32 v231, v33
	s_nop 1
	v_permlane32_swap_b32_e32 v228, v230
	v_permlane32_swap_b32_e32 v229, v231
	global_store_dwordx4 v[234:235], v[228:231], off offset:64
	v_lshlrev_b32_e32 v32, 16, v168
	v_and_b32_e32 v33, 0xffff0000, v168
	v_mul_f32_e32 v34, 0xbfb8aa3b, v32
	v_mul_f32_e32 v35, 0xbfb8aa3b, v33
	v_exp_f32_e32 v34, v34
	v_exp_f32_e32 v35, v35
	v_pk_mul_f32 v[38:39], v[42:43], v[64:65] op_sel_hi:[1,0]
	v_add_f32_e32 v34, 1.0, v34
	v_add_f32_e32 v35, 1.0, v35
	v_rcp_f32_e32 v34, v34
	v_rcp_f32_e32 v35, v35
	s_nop 0
	v_pk_mul_f32 v[32:33], v[34:35], v[32:33]
	s_nop 0
	v_pk_mul_f32 v[32:33], v[32:33], v[36:37]
	v_lshlrev_b32_e32 v34, 16, v169
	v_cvt_pk_bf16_f32 v32, v32, v33
	v_mul_f32_e32 v33, 0xbfb8aa3b, v34
	v_exp_f32_e32 v33, v33
	v_and_b32_e32 v35, 0xffff0000, v169
	v_add_f32_e32 v33, 1.0, v33
	v_rcp_f32_e32 v36, v33
	v_mul_f32_e32 v33, 0xbfb8aa3b, v35
	v_exp_f32_e32 v33, v33
	s_nop 0
	v_add_f32_e32 v33, 1.0, v33
	v_rcp_f32_e32 v37, v33
	s_nop 0
	v_pk_mul_f32 v[34:35], v[36:37], v[34:35]
	s_nop 0
	v_pk_mul_f32 v[34:35], v[34:35], v[38:39]
	v_pk_mul_f32 v[36:37], v[44:45], v[64:65] op_sel_hi:[1,0]
	v_cvt_pk_bf16_f32 v33, v34, v35
	v_mov_b32_e32 v228, v32
	v_mov_b32_e32 v229, v33
	v_lshlrev_b32_e32 v32, 16, v166
	v_and_b32_e32 v33, 0xffff0000, v166
	v_mul_f32_e32 v34, 0xbfb8aa3b, v32
	v_mul_f32_e32 v35, 0xbfb8aa3b, v33
	v_exp_f32_e32 v34, v34
	v_exp_f32_e32 v35, v35
	v_pk_mul_f32 v[38:39], v[46:47], v[64:65] op_sel_hi:[1,0]
	v_add_f32_e32 v34, 1.0, v34
	v_add_f32_e32 v35, 1.0, v35
	v_rcp_f32_e32 v34, v34
	v_rcp_f32_e32 v35, v35
	s_nop 0
	v_pk_mul_f32 v[32:33], v[34:35], v[32:33]
	s_nop 0
	v_pk_mul_f32 v[32:33], v[32:33], v[36:37]
	v_lshlrev_b32_e32 v34, 16, v167
	v_cvt_pk_bf16_f32 v32, v32, v33
	v_mul_f32_e32 v33, 0xbfb8aa3b, v34
	v_exp_f32_e32 v33, v33
	v_and_b32_e32 v35, 0xffff0000, v167
	v_add_f32_e32 v33, 1.0, v33
	v_rcp_f32_e32 v36, v33
	v_mul_f32_e32 v33, 0xbfb8aa3b, v35
	v_exp_f32_e32 v33, v33
	s_nop 0
	v_add_f32_e32 v33, 1.0, v33
	v_rcp_f32_e32 v37, v33
	s_nop 0
	v_pk_mul_f32 v[34:35], v[36:37], v[34:35]
	s_nop 0
	v_pk_mul_f32 v[34:35], v[34:35], v[38:39]
	v_and_b32_e32 v37, 0xffff0000, v162
	v_cvt_pk_bf16_f32 v33, v34, v35
	v_mov_b32_e32 v230, v32
	v_mov_b32_e32 v231, v33
	s_nop 1
	v_permlane32_swap_b32_e32 v228, v230
	v_permlane32_swap_b32_e32 v229, v231
	global_store_dwordx4 v[234:235], v[228:231], off offset:96
	v_lshlrev_b64 v[32:33], 12, v[164:165]
	v_lshl_add_u64 v[32:33], s[42:43], 0, v[32:33]
	v_lshl_add_u64 v[34:35], v[32:33], 0, s[70:71]
	v_max_f32_e32 v33, v191, v191
	v_max_f32_e32 v33, v33, v66
	v_sub_f32_e32 v36, v191, v33
	v_fma_f32 v33, v65, s6, -v33
	v_exp_f32_e32 v36, v36
	v_exp_f32_e32 v33, v33
	v_mov_b32_e32 v32, v190
	s_nop 1
	v_permlane32_swap_b32_e32 v190, v32
	v_add_f32_e32 v32, v190, v32
	v_fmac_f32_e32 v33, v36, v32
	v_rcp_f32_e32 v32, v33
	s_and_b32 s6, s40, -2
	s_add_i32 s52, s10, s6
	s_lshl_b32 s40, s40, 7
	v_mul_f32_e32 v32, v36, v32
	v_lshlrev_b32_e32 v36, 16, v162
	v_mul_f32_e32 v33, 0xbfb8aa3b, v36
	v_exp_f32_e32 v33, v33
	s_and_b32 s40, s40, 0x3fffff00
	v_mov_b32_e32 v162, 0xf149f2ca
	v_add_f32_e32 v33, 1.0, v33
	v_rcp_f32_e32 v38, v33
	v_pk_mul_f32 v[16:17], v[16:17], v[32:33] op_sel_hi:[1,0]
	v_mul_f32_e32 v33, 0xbfb8aa3b, v37
	v_exp_f32_e32 v33, v33
	s_nop 0
	v_add_f32_e32 v33, 1.0, v33
	v_rcp_f32_e32 v39, v33
	s_nop 0
	v_pk_mul_f32 v[36:37], v[38:39], v[36:37]
	s_nop 0
	v_pk_mul_f32 v[16:17], v[36:37], v[16:17]
	s_nop 0
	v_cvt_pk_bf16_f32 v36, v16, v17
	v_lshlrev_b32_e32 v16, 16, v163
; __device__ __forceinline__ unsigned cvt_pk_bf16(float lo, float hi) { f32x2_c v = {lo, hi}; bf16x2_c b = __builtin_convertvector(v, bf16x2_c); return __builtin_bit_cast(unsigned, b); }
; __device__ __forceinline__ float silu_f(float z) { return z * __builtin_amdgcn_rcpf(1.f + __expf(-z)); }
; __device__ __forceinline__ void la_store(const LA& st, bool use_sink, float sink2, const u32x2 (&zv)[8], bf16_t* yrow, int hi) {
;     float l = st.l; { auto rr = __builtin_amdgcn_permlane32_swap(__float_as_uint(l), __float_as_uint(l), false, false); l = __uint_as_float(rr[0]) + __uint_as_float(rr[1]); }
;     float inv;
;     if (use_sink) { const float m2 = fmaxf(st.m, sink2), a = __builtin_amdgcn_exp2f(st.m - m2); inv = a * __builtin_amdgcn_rcpf(l * a + __builtin_amdgcn_exp2f(sink2 - m2)); }
;     else inv = __builtin_amdgcn_rcpf(l);
; #pragma unroll
;     for (int db = 0; db < 2; ++db)
; #pragma unroll
;         for (int g = 0; g < 4; ++g) { const int c = 32 * db + 8 * g + 4 * hi; const u32x2 z = zv[4 * db + g];
;             const f32x16& o = db ? st.o1 : st.o0;
;             u32x2 w; w.x = cvt_pk_bf16(o[4 * g] * inv * silu_f(bf_lo(z.x)), o[4 * g + 1] * inv * silu_f(bf_hi(z.x)));
;             w.y = cvt_pk_bf16(o[4 * g + 2] * inv * silu_f(bf_lo(z.y)), o[4 * g + 3] * inv * silu_f(bf_hi(z.y)));
;             *(u32x2*)(yrow + c) = w; }
; __global__ void __launch_bounds__(NWAVES * 64, 2) mk_fwd(Args args) {
;     ...
;                 la_store(sa, true, sk2, za, Yb + (size_t)tqa * DMODEL + h * 64, hi);
;                 la_store(sb, true, sk2, zb, Yb + (size_t)tqb * DMODEL + h * 64, hi);
	v_mul_f32_e32 v33, 0xbfb8aa3b, v16
	v_exp_f32_e32 v33, v33
	v_and_b32_e32 v17, 0xffff0000, v163
	v_or_b32_e32 v163, s55, v186
	v_add_f32_e32 v33, 1.0, v33
	v_rcp_f32_e32 v38, v33
	v_pk_mul_f32 v[18:19], v[18:19], v[32:33] op_sel_hi:[1,0]
	v_mul_f32_e32 v33, 0xbfb8aa3b, v17
	v_exp_f32_e32 v33, v33
	s_nop 0
	v_add_f32_e32 v33, 1.0, v33
	v_rcp_f32_e32 v39, v33
	s_nop 0
	v_pk_mul_f32 v[16:17], v[38:39], v[16:17]
	s_nop 0
	v_pk_mul_f32 v[16:17], v[16:17], v[18:19]
	v_lshlrev_b32_e32 v18, 16, v160
	v_mul_f32_e32 v33, 0xbfb8aa3b, v18
	v_exp_f32_e32 v33, v33
	v_and_b32_e32 v19, 0xffff0000, v160
	v_cvt_pk_bf16_f32 v37, v16, v17
	v_lshl_add_u64 v[16:17], v[34:35], 0, v[144:145]
	v_add_f32_e32 v33, 1.0, v33
	v_rcp_f32_e32 v34, v33
	v_pk_mul_f32 v[20:21], v[20:21], v[32:33] op_sel_hi:[1,0]
	v_mul_f32_e32 v33, 0xbfb8aa3b, v19
	v_exp_f32_e32 v33, v33
	v_lshrrev_b32_e32 v236, 2, v252
	v_and_b32_e32 v236, 8, v236
	v_add_u32_e32 v234, v16, v236
	v_mov_b32_e32 v235, v17
	v_mov_b32_e32 v228, v36
	v_mov_b32_e32 v229, v37
	v_mov_b32_e32 v145, 0xf149f2ca
	v_add_f32_e32 v33, 1.0, v33
	v_rcp_f32_e32 v35, v33
	v_pk_mul_f32 v[22:23], v[22:23], v[32:33] op_sel_hi:[1,0]
	v_pk_mul_f32 v[0:1], v[0:1], v[32:33] op_sel_hi:[1,0]
	v_pk_mul_f32 v[2:3], v[2:3], v[32:33] op_sel_hi:[1,0]
	v_pk_mul_f32 v[18:19], v[34:35], v[18:19]
	v_pk_mul_f32 v[4:5], v[4:5], v[32:33] op_sel_hi:[1,0]
	v_pk_mul_f32 v[18:19], v[18:19], v[20:21]
	v_lshlrev_b32_e32 v20, 16, v161
	v_cvt_pk_bf16_f32 v18, v18, v19
	v_mul_f32_e32 v19, 0xbfb8aa3b, v20
	v_exp_f32_e32 v19, v19
	v_and_b32_e32 v21, 0xffff0000, v161
	v_pk_mul_f32 v[6:7], v[6:7], v[32:33] op_sel_hi:[1,0]
	v_add_f32_e32 v19, 1.0, v19
	v_rcp_f32_e32 v34, v19
	v_mul_f32_e32 v19, 0xbfb8aa3b, v21
	v_exp_f32_e32 v19, v19
	s_nop 0
	v_add_f32_e32 v19, 1.0, v19
	v_rcp_f32_e32 v35, v19
	s_nop 0
	v_pk_mul_f32 v[20:21], v[34:35], v[20:21]
	s_nop 0
	v_pk_mul_f32 v[20:21], v[20:21], v[22:23]
	v_pk_mul_f32 v[22:23], v[24:25], v[32:33] op_sel_hi:[1,0]
	v_cvt_pk_bf16_f32 v19, v20, v21
	v_mov_b32_e32 v230, v18
	v_mov_b32_e32 v231, v19
	s_nop 1
	v_permlane32_swap_b32_e32 v228, v230
	v_permlane32_swap_b32_e32 v229, v231
	global_store_dwordx4 v[234:235], v[228:231], off
	v_lshlrev_b32_e32 v18, 16, v158
	v_and_b32_e32 v19, 0xffff0000, v158
	v_mul_f32_e32 v20, 0xbfb8aa3b, v18
	v_mul_f32_e32 v21, 0xbfb8aa3b, v19
	v_exp_f32_e32 v20, v20
	v_exp_f32_e32 v21, v21
	v_pk_mul_f32 v[24:25], v[26:27], v[32:33] op_sel_hi:[1,0]
	v_add_f32_e32 v20, 1.0, v20
	v_add_f32_e32 v21, 1.0, v21
	v_rcp_f32_e32 v20, v20
	v_rcp_f32_e32 v21, v21
	s_nop 0
	v_pk_mul_f32 v[18:19], v[20:21], v[18:19]
	s_nop 0
	v_pk_mul_f32 v[18:19], v[18:19], v[22:23]
	v_lshlrev_b32_e32 v20, 16, v159
	v_cvt_pk_bf16_f32 v18, v18, v19
	v_mul_f32_e32 v19, 0xbfb8aa3b, v20
	v_exp_f32_e32 v19, v19
	v_and_b32_e32 v21, 0xffff0000, v159
	v_add_f32_e32 v19, 1.0, v19
	v_rcp_f32_e32 v22, v19
	v_mul_f32_e32 v19, 0xbfb8aa3b, v21
	v_exp_f32_e32 v19, v19
	s_nop 0
	v_add_f32_e32 v19, 1.0, v19
	v_rcp_f32_e32 v23, v19
	s_nop 0
	v_pk_mul_f32 v[20:21], v[22:23], v[20:21]
	s_nop 0
	v_pk_mul_f32 v[20:21], v[20:21], v[24:25]
	v_pk_mul_f32 v[22:23], v[28:29], v[32:33] op_sel_hi:[1,0]
	v_cvt_pk_bf16_f32 v19, v20, v21
	v_mov_b32_e32 v228, v18
	v_mov_b32_e32 v229, v19
	v_lshlrev_b32_e32 v18, 16, v156
	v_and_b32_e32 v19, 0xffff0000, v156
	v_mul_f32_e32 v20, 0xbfb8aa3b, v18
	v_mul_f32_e32 v21, 0xbfb8aa3b, v19
	v_exp_f32_e32 v20, v20
	v_exp_f32_e32 v21, v21
	v_pk_mul_f32 v[24:25], v[30:31], v[32:33] op_sel_hi:[1,0]
	v_mov_b32_e32 v156, 0
	v_add_f32_e32 v20, 1.0, v20
	v_add_f32_e32 v21, 1.0, v21
	v_rcp_f32_e32 v20, v20
	v_rcp_f32_e32 v21, v21
	s_nop 0
	v_pk_mul_f32 v[18:19], v[20:21], v[18:19]
	s_nop 0
	v_pk_mul_f32 v[18:19], v[18:19], v[22:23]
	v_lshlrev_b32_e32 v20, 16, v157
	v_cvt_pk_bf16_f32 v18, v18, v19
	v_mul_f32_e32 v19, 0xbfb8aa3b, v20
	v_exp_f32_e32 v19, v19
	v_and_b32_e32 v21, 0xffff0000, v157
	v_mov_b32_e32 v157, 0
	v_add_f32_e32 v19, 1.0, v19
	v_rcp_f32_e32 v22, v19
	v_mul_f32_e32 v19, 0xbfb8aa3b, v21
	v_exp_f32_e32 v19, v19
	s_nop 0
	v_add_f32_e32 v19, 1.0, v19
	v_rcp_f32_e32 v23, v19
	s_nop 0
	v_pk_mul_f32 v[20:21], v[22:23], v[20:21]
	s_nop 0
	v_pk_mul_f32 v[20:21], v[20:21], v[24:25]
	s_nop 0
	v_cvt_pk_bf16_f32 v19, v20, v21
	v_mov_b32_e32 v230, v18
	v_mov_b32_e32 v231, v19
	s_nop 1
	v_permlane32_swap_b32_e32 v228, v230
	v_permlane32_swap_b32_e32 v229, v231
	global_store_dwordx4 v[234:235], v[228:231], off offset:32
	v_lshlrev_b32_e32 v18, 16, v154
	v_and_b32_e32 v19, 0xffff0000, v154
	v_mul_f32_e32 v20, 0xbfb8aa3b, v18
	v_mul_f32_e32 v21, 0xbfb8aa3b, v19
	v_exp_f32_e32 v20, v20
	v_exp_f32_e32 v21, v21
	v_add_f32_e32 v20, 1.0, v20
	v_add_f32_e32 v21, 1.0, v21
	v_rcp_f32_e32 v20, v20
	v_rcp_f32_e32 v21, v21
	s_nop 0
	v_pk_mul_f32 v[18:19], v[20:21], v[18:19]
	s_nop 0
	v_pk_mul_f32 v[0:1], v[18:19], v[0:1]
	v_lshlrev_b32_e32 v18, 16, v155
	v_cvt_pk_bf16_f32 v0, v0, v1
	v_mul_f32_e32 v1, 0xbfb8aa3b, v18
	v_exp_f32_e32 v1, v1
	v_and_b32_e32 v19, 0xffff0000, v155
	v_add_f32_e32 v1, 1.0, v1
	v_rcp_f32_e32 v20, v1
	v_mul_f32_e32 v1, 0xbfb8aa3b, v19
	v_exp_f32_e32 v1, v1
	s_nop 0
	v_add_f32_e32 v1, 1.0, v1
	v_rcp_f32_e32 v21, v1
	s_nop 0
	v_pk_mul_f32 v[18:19], v[20:21], v[18:19]
	s_nop 0
	v_pk_mul_f32 v[2:3], v[18:19], v[2:3]
	s_nop 0
	v_cvt_pk_bf16_f32 v1, v2, v3
	v_mov_b32_e32 v228, v0
	v_mov_b32_e32 v229, v1
	v_lshlrev_b32_e32 v0, 16, v152
	v_and_b32_e32 v1, 0xffff0000, v152
	v_mul_f32_e32 v2, 0xbfb8aa3b, v0
	v_mul_f32_e32 v3, 0xbfb8aa3b, v1
	v_exp_f32_e32 v2, v2
	v_exp_f32_e32 v3, v3
	v_add_f32_e32 v2, 1.0, v2
	v_add_f32_e32 v3, 1.0, v3
	v_rcp_f32_e32 v2, v2
	v_rcp_f32_e32 v3, v3
	s_nop 0
	v_pk_mul_f32 v[0:1], v[2:3], v[0:1]
; #define LAS __attribute__((address_space(3)))
; __device__ __forceinline__ float silu_f(float z) { return z * __builtin_amdgcn_rcpf(1.f + __expf(-z)); }
; __device__ __forceinline__ void la_store(const LA& st, bool use_sink, float sink2, const u32x2 (&zv)[8], bf16_t* yrow, int hi) {
;     float l = st.l; { auto rr = __builtin_amdgcn_permlane32_swap(__float_as_uint(l), __float_as_uint(l), false, false); l = __uint_as_float(rr[0]) + __uint_as_float(rr[1]); }
;     float inv;
;     if (use_sink) { const float m2 = fmaxf(st.m, sink2), a = __builtin_amdgcn_exp2f(st.m - m2); inv = a * __builtin_amdgcn_rcpf(l * a + __builtin_amdgcn_exp2f(sink2 - m2)); }
;     else inv = __builtin_amdgcn_rcpf(l);
; #pragma unroll
;     for (int db = 0; db < 2; ++db)
; #pragma unroll
;         for (int g = 0; g < 4; ++g) { const int c = 32 * db + 8 * g + 4 * hi; const u32x2 z = zv[4 * db + g];
;             const f32x16& o = db ? st.o1 : st.o0;
;             u32x2 w; w.x = cvt_pk_bf16(o[4 * g] * inv * silu_f(bf_lo(z.x)), o[4 * g + 1] * inv * silu_f(bf_hi(z.x)));
;             w.y = cvt_pk_bf16(o[4 * g + 2] * inv * silu_f(bf_lo(z.y)), o[4 * g + 3] * inv * silu_f(bf_hi(z.y)));
;             *(u32x2*)(yrow + c) = w; }
; __global__ void __launch_bounds__(NWAVES * 64, 2) mk_fwd(Args args) {
;     ...
;                 const int qh = wave & 1, qrow = 8 * v32 + 2 * (wave >> 1), qc = 32 * qh + r32, tqa = 64 * qrow + qc, tqb = tqa + 64;
;                 int rsa = qrow - 4; rsa = rsa < 0 ? 0 : (rsa > 248 ? 248 : rsa); int rsb = qrow - 3; rsb = rsb < 0 ? 0 : (rsb > 248 ? 248 : rsb); int cs = qc - 8; cs = cs < 0 ? 0 : (cs > 48 ? 48 : cs);
;                 bf16x8 qa[4], qb[4]; const bf16_t* qp = PROJ + (size_t)tqa * PP + C_QB + h * 64 + 8 * hi;
; #pragma unroll
;                 for (int d0 = 0; d0 < 4; ++d0) { qa[d0] = *(const bf16x8*)(qp + 16 * d0); qb[d0] = *(const bf16x8*)(qp + (size_t)64 * PP + 16 * d0); }
;                 LA sa, sb; sa.o0 = zero16(); sa.o1 = sa.o0; sa.m = NEGBIG; sa.l = 0.f; sb.o0 = zero16(); sb.o1 = sb.o0; sb.m = NEGBIG; sb.l = 0.f;
;                 const int vd = h * 64 + r32; const unsigned kc = (unsigned)(C_KB + h * 64 + 8 * hi);
;                 const VSG vs{(const char*)VTB};
;                 const LAS char* bb0 = (const LAS char*)(tabB + ((7 - qrow) * 128 + 32 * qh + 8 * hi - qc + 64));
;                 const int cbr = 32 * qh + 8 * hi - cs;
	s_nop 0
	v_pk_mul_f32 v[0:1], v[0:1], v[4:5]
	v_lshlrev_b32_e32 v2, 16, v153
	v_cvt_pk_bf16_f32 v0, v0, v1
	v_mul_f32_e32 v1, 0xbfb8aa3b, v2
	v_exp_f32_e32 v1, v1
	v_and_b32_e32 v3, 0xffff0000, v153
	v_add_f32_e32 v1, 1.0, v1
	v_rcp_f32_e32 v4, v1
	v_mul_f32_e32 v1, 0xbfb8aa3b, v3
	v_exp_f32_e32 v1, v1
	s_nop 0
	v_add_f32_e32 v1, 1.0, v1
	v_rcp_f32_e32 v5, v1
	s_nop 0
	v_pk_mul_f32 v[2:3], v[4:5], v[2:3]
	s_nop 0
	v_pk_mul_f32 v[2:3], v[2:3], v[6:7]
	v_pk_mul_f32 v[4:5], v[8:9], v[32:33] op_sel_hi:[1,0]
	v_cvt_pk_bf16_f32 v1, v2, v3
	v_mov_b32_e32 v230, v0
	v_mov_b32_e32 v231, v1
	s_nop 1
	v_permlane32_swap_b32_e32 v228, v230
	v_permlane32_swap_b32_e32 v229, v231
	global_store_dwordx4 v[234:235], v[228:231], off offset:64
	v_lshlrev_b32_e32 v0, 16, v150
	v_and_b32_e32 v1, 0xffff0000, v150
	v_mul_f32_e32 v2, 0xbfb8aa3b, v0
	v_mul_f32_e32 v3, 0xbfb8aa3b, v1
	v_exp_f32_e32 v2, v2
	v_exp_f32_e32 v3, v3
	v_pk_mul_f32 v[6:7], v[10:11], v[32:33] op_sel_hi:[1,0]
	v_add_f32_e32 v2, 1.0, v2
	v_add_f32_e32 v3, 1.0, v3
	v_rcp_f32_e32 v2, v2
	v_rcp_f32_e32 v3, v3
	s_nop 0
	v_pk_mul_f32 v[0:1], v[2:3], v[0:1]
	s_nop 0
	v_pk_mul_f32 v[0:1], v[0:1], v[4:5]
	v_lshlrev_b32_e32 v2, 16, v151
	v_cvt_pk_bf16_f32 v0, v0, v1
	v_mul_f32_e32 v1, 0xbfb8aa3b, v2
	v_exp_f32_e32 v1, v1
	v_and_b32_e32 v3, 0xffff0000, v151
	v_add_f32_e32 v1, 1.0, v1
	v_rcp_f32_e32 v4, v1
	v_mul_f32_e32 v1, 0xbfb8aa3b, v3
	v_exp_f32_e32 v1, v1
	s_nop 0
	v_add_f32_e32 v1, 1.0, v1
	v_rcp_f32_e32 v5, v1
	s_nop 0
	v_pk_mul_f32 v[2:3], v[4:5], v[2:3]
	s_nop 0
	v_pk_mul_f32 v[2:3], v[2:3], v[6:7]
	v_pk_mul_f32 v[4:5], v[12:13], v[32:33] op_sel_hi:[1,0]
	v_cvt_pk_bf16_f32 v1, v2, v3
	v_mov_b32_e32 v228, v0
	v_mov_b32_e32 v229, v1
	v_lshlrev_b32_e32 v0, 16, v148
	v_and_b32_e32 v1, 0xffff0000, v148
	v_mul_f32_e32 v2, 0xbfb8aa3b, v0
	v_mul_f32_e32 v3, 0xbfb8aa3b, v1
	v_exp_f32_e32 v2, v2
	v_exp_f32_e32 v3, v3
	v_pk_mul_f32 v[6:7], v[14:15], v[32:33] op_sel_hi:[1,0]
	v_lshl_or_b32 v148, s52, 6, v163
	v_add_f32_e32 v2, 1.0, v2
	v_add_f32_e32 v3, 1.0, v3
	v_rcp_f32_e32 v2, v2
	v_rcp_f32_e32 v3, v3
	s_nop 0
	v_pk_mul_f32 v[0:1], v[2:3], v[0:1]
	s_nop 0
	v_pk_mul_f32 v[0:1], v[0:1], v[4:5]
	v_lshlrev_b32_e32 v2, 16, v149
	v_cvt_pk_bf16_f32 v0, v0, v1
	v_mul_f32_e32 v1, 0xbfb8aa3b, v2
	v_exp_f32_e32 v1, v1
	v_and_b32_e32 v3, 0xffff0000, v149
	v_ashrrev_i32_e32 v149, 31, v148
	v_add_f32_e32 v1, 1.0, v1
	v_rcp_f32_e32 v4, v1
	v_mul_f32_e32 v1, 0xbfb8aa3b, v3
	v_exp_f32_e32 v1, v1
	s_nop 0
	v_add_f32_e32 v1, 1.0, v1
	v_rcp_f32_e32 v5, v1
	s_nop 0
	v_pk_mul_f32 v[2:3], v[4:5], v[2:3]
	s_nop 0
	v_pk_mul_f32 v[2:3], v[2:3], v[6:7]
	v_med3_i32 v4, v163, 8, 56
	v_cvt_pk_bf16_f32 v1, v2, v3
	v_mov_b32_e32 v230, v0
	v_mov_b32_e32 v231, v1
	s_nop 1
	v_permlane32_swap_b32_e32 v228, v230
	v_permlane32_swap_b32_e32 v229, v231
	global_store_dwordx4 v[234:235], v[228:231], off offset:96
	v_bfrev_b32_e32 v0, 0.5
	v_med3_i32 v160, s52, 4, v0
	v_mov_b32_e32 v0, 0xfb
	v_med3_i32 v158, s52, 3, v0
	v_mov_b64_e32 v[0:1], s[74:75]
	v_mad_i64_i32 v[0:1], s[6:7], v148, s64, v[0:1]
	v_lshl_add_u64 v[150:151], v[0:1], 0, s[70:71]
	v_readfirstlane_b32 s59, v160
	v_lshl_add_u64 v[0:1], v[150:151], 0, v[188:189]
	s_mov_b32 s6, 0xd2000
	s_add_i32 s59, s59, -4
	v_add_co_u32_e32 v2, vcc, s6, v0
	v_or_b32_e32 v16, s30, v186
	s_lshl_b32 s61, s59, 6
	v_addc_co_u32_e32 v3, vcc, 0, v1, vcc
	s_or_b32 s41, s61, s55
	v_lshrrev_b32_e32 v16, 1, v16
	global_load_dwordx4 v[96:99], v[0:1], off offset:2560
	global_load_dwordx4 v[80:83], v[2:3], off offset:2560
	global_load_dwordx4 v[100:103], v[0:1], off offset:2592
	global_load_dwordx4 v[84:87], v[2:3], off offset:2592
	global_load_dwordx4 v[104:107], v[0:1], off offset:2624
	global_load_dwordx4 v[88:91], v[2:3], off offset:2624
	global_load_dwordx4 v[108:111], v[0:1], off offset:2656
	global_load_dwordx4 v[92:95], v[2:3], off offset:2656
	s_add_i32 s6, s30, 0x700
	v_mul_lo_u32 v154, v16, s65
	v_or_b32_e32 v16, s41, v185
	v_or_b32_e32 v161, s6, v146
	v_mul_i32_i24_e32 v16, 0x1a40, v16
	v_add_lshl_u32 v16, v16, v161, 1
	v_mov_b32 v32, 0
	v_mov_b32 v0, 0
	global_load_dwordx4 v[124:127], v16, s[74:75]
	global_load_dwordx4 v[120:123], v16, s[74:75] offset:32
	global_load_dwordx4 v[116:119], v16, s[74:75] offset:64
	global_load_dwordx4 v[112:115], v16, s[74:75] offset:96
	v_add_u32_e32 v152, -8, v4
	v_or_b32_e32 v17, s55, v146
	v_sub_u32_e32 v17, v17, v152
	v_add_u32_e32 v16, 1, v17
	v_cmp_gt_u32_e64 s[8:9], 16, v16
	v_add_u32_e32 v16, 2, v17
	v_cmp_gt_u32_e64 s[10:11], 16, v16
	v_add_u32_e32 v16, 3, v17
	v_cmp_gt_u32_e64 s[12:13], 16, v16
	v_add_u32_e32 v16, 4, v17
	v_cmp_gt_u32_e64 s[14:15], 16, v16
	v_add_u32_e32 v16, 5, v17
	v_cmp_gt_u32_e64 s[16:17], 16, v16
	v_add_u32_e32 v16, 6, v17
	v_cmp_gt_u32_e64 s[18:19], 16, v16
	v_add_u32_e32 v16, 7, v17
	v_cmp_gt_u32_e64 s[20:21], 16, v16
	v_add_u32_e32 v16, 17, v17
	v_cmp_gt_u32_e64 s[24:25], 16, v16
	v_add_u32_e32 v16, 18, v17
	v_cmp_gt_u32_e64 s[26:27], 16, v16
	v_add_u32_e32 v16, 19, v17
	v_cmp_gt_u32_e64 s[28:29], 16, v16
	v_add_u32_e32 v16, 20, v17
	v_cmp_gt_u32_e64 s[30:31], 16, v16
	v_add_u32_e32 v16, 21, v17
	v_cmp_gt_u32_e64 s[34:35], 16, v16
	v_add_u32_e32 v16, 22, v17
	v_cmp_gt_u32_e64 s[36:37], 16, v16
	v_add_u32_e32 v16, 23, v17
	v_cmp_gt_u32_e64 s[6:7], 16, v17
	v_cmp_lt_u32_e64 s[22:23], s22, v17
	v_cmp_gt_u32_e64 s[38:39], 16, v16
	v_lshlrev_b32_e32 v16, 9, v160
	v_sub_u32_e32 v17, v146, v186
	v_subrev_u32_e32 v17, s40, v17
	v_add_u32_e32 v16, 0, v16
	v_mov_b32_e32 v46, v32
	v_mov_b32_e32 v47, v32
	v_mov_b32_e32 v14, v0
	v_mov_b32_e32 v15, v0
	v_or_b32_e32 v164, v154, v147
	v_subrev_u32_e32 v17, s0, v17
	v_add_u32_e32 v16, 0x6720, v16
	v_mov_b32_e32 v33, v32
	v_mov_b32_e32 v34, v32
	v_mov_b32_e32 v35, v32
	v_mov_b32_e32 v36, v32
	v_mov_b32_e32 v37, v32
	v_mov_b32_e32 v38, v32
	v_mov_b32_e32 v39, v32
	v_mov_b32_e32 v40, v32
	v_mov_b32_e32 v41, v32
	v_mov_b32_e32 v42, v32
	v_mov_b32_e32 v43, v32
	v_mov_b32_e32 v44, v32
	v_mov_b32_e32 v45, v32
	v_mov_b32_e32 v1, v0
	v_mov_b32_e32 v2, v0
	v_mov_b32_e32 v3, v0
	v_mov_b32_e32 v4, v0
	v_mov_b32_e32 v5, v0
	v_mov_b32_e32 v6, v0
	v_mov_b32_e32 v7, v0
	v_mov_b32_e32 v8, v0
	v_mov_b32_e32 v9, v0
	v_mov_b32_e32 v10, v0
	v_mov_b32_e32 v11, v0
	v_mov_b32_e32 v12, v0
	v_mov_b32_e32 v13, v0
	v_or_b32_e32 v155, v164, v146
	v_lshl_add_u32 v167, v17, 2, v16
	v_mov_b64_e32 v[62:63], v[46:47]
	v_mov_b64_e32 v[30:31], v[14:15]
	v_add_u32_e32 v159, -3, v158
	v_add_u32_e32 v153, 5, v158
	v_lshlrev_b32_e32 v165, 1, v155
	v_mov_b64_e32 v[60:61], v[44:45]
	v_mov_b64_e32 v[58:59], v[42:43]
	v_mov_b64_e32 v[56:57], v[40:41]
	v_mov_b64_e32 v[54:55], v[38:39]
	v_mov_b64_e32 v[52:53], v[36:37]
	v_mov_b64_e32 v[50:51], v[34:35]
	v_mov_b64_e32 v[48:49], v[32:33]
	v_mov_b64_e32 v[28:29], v[12:13]
	v_mov_b64_e32 v[26:27], v[10:11]
	v_mov_b64_e32 v[24:25], v[8:9]
	v_mov_b64_e32 v[22:23], v[6:7]
	v_mov_b64_e32 v[20:21], v[4:5]
	v_mov_b64_e32 v[18:19], v[2:3]
	v_mov_b64_e32 v[16:17], v[0:1]

; __device__ __forceinline__ unsigned cvt_pk_bf16(float lo, float hi) { f32x2_c v = {lo, hi}; bf16x2_c b = __builtin_convertvector(v, bf16x2_c); return __builtin_bit_cast(unsigned, b); }
; __device__ __forceinline__ float silu_f(float z) { return z * __builtin_amdgcn_rcpf(1.f + __expf(-z)); }
; __device__ __forceinline__ void la_loadz(u32x2 (&z)[8], const bf16_t* zrow, int hi) {
; #pragma unroll
;     for (int db = 0; db < 2; ++db)
; #pragma unroll
;         for (int g = 0; g < 4; ++g) z[4 * db + g] = *(const u32x2*)(zrow + 32 * db + 8 * g + 4 * hi);
; }
; __device__ __forceinline__ void la_store(const LA& st, bool use_sink, float sink2, const u32x2 (&zv)[8], bf16_t* yrow, int hi) {
;     float l = st.l; { auto rr = __builtin_amdgcn_permlane32_swap(__float_as_uint(l), __float_as_uint(l), false, false); l = __uint_as_float(rr[0]) + __uint_as_float(rr[1]); }
;     float inv;
;     if (use_sink) { const float m2 = fmaxf(st.m, sink2), a = __builtin_amdgcn_exp2f(st.m - m2); inv = a * __builtin_amdgcn_rcpf(l * a + __builtin_amdgcn_exp2f(sink2 - m2)); }
;     else inv = __builtin_amdgcn_rcpf(l);
; #pragma unroll
;     for (int db = 0; db < 2; ++db)
; #pragma unroll
;         for (int g = 0; g < 4; ++g) { const int c = 32 * db + 8 * g + 4 * hi; const u32x2 z = zv[4 * db + g];
;             const f32x16& o = db ? st.o1 : st.o0;
;             u32x2 w; w.x = cvt_pk_bf16(o[4 * g] * inv * silu_f(bf_lo(z.x)), o[4 * g + 1] * inv * silu_f(bf_hi(z.x)));
;             w.y = cvt_pk_bf16(o[4 * g + 2] * inv * silu_f(bf_lo(z.y)), o[4 * g + 3] * inv * silu_f(bf_hi(z.y)));
;             *(u32x2*)(yrow + c) = w; }
; __global__ void __launch_bounds__(NWAVES * 64, 2) mk_fwd(Args args) {
;     ...
;                 u32x2 zv[8];
;                 la_loadz(zv, PROJ + (size_t)tqa * PP + C_ZB + h * 64, hi); la_store(sa, false, 0.f, zv, Yb + (size_t)tqa * DMODEL + 512 + h * 64, hi);
.LBB0_694:
	v_mov_b32_e32 v145, v189
	v_lshl_add_u64 v[66:67], v[150:151], 0, v[144:145]
	s_mov_b64 s[8:9], 0x1600
	v_lshl_add_u64 v[70:71], v[66:67], 0, s[8:9]
	v_add_co_u32_e32 v66, vcc, 0x1000, v66
	v_mov_b32_e32 v65, v157
	s_nop 0
	v_addc_co_u32_e32 v67, vcc, 0, v67, vcc
	global_load_dwordx2 v[82:83], v[66:67], off offset:1536
	global_load_dwordx2 v[80:81], v[70:71], off offset:16
	global_load_dwordx2 v[78:79], v[70:71], off offset:32
	global_load_dwordx2 v[76:77], v[70:71], off offset:48
	global_load_dwordx2 v[74:75], v[70:71], off offset:64
	global_load_dwordx2 v[72:73], v[70:71], off offset:80
	global_load_dwordx2 v[68:69], v[70:71], off offset:96
	global_load_dwordx2 v[66:67], v[70:71], off offset:112
	v_lshlrev_b64 v[70:71], 12, v[148:149]
	v_permlane32_swap_b32_e32 v157, v65
	v_lshl_add_u64 v[70:71], s[42:43], 0, v[70:71]
	v_add_f32_e32 v65, v157, v65
	v_lshl_add_u64 v[84:85], v[70:71], 0, s[70:71]
	v_rcp_f32_e32 v70, v65
	v_or_b32_e32 v64, 64, v148
	s_movk_i32 s0, 0x1000
	v_lshlrev_b32_e32 v157, 4, v185
	v_pk_mul_f32 v[48:49], v[48:49], v[70:71] op_sel_hi:[1,0]
	v_pk_mul_f32 v[50:51], v[50:51], v[70:71] op_sel_hi:[1,0]
	v_pk_mul_f32 v[52:53], v[52:53], v[70:71] op_sel_hi:[1,0]
	v_pk_mul_f32 v[54:55], v[54:55], v[70:71] op_sel_hi:[1,0]
	v_pk_mul_f32 v[32:33], v[32:33], v[70:71] op_sel_hi:[1,0]
	v_pk_mul_f32 v[34:35], v[34:35], v[70:71] op_sel_hi:[1,0]
	v_pk_mul_f32 v[36:37], v[36:37], v[70:71] op_sel_hi:[1,0]
	v_pk_mul_f32 v[38:39], v[38:39], v[70:71] op_sel_hi:[1,0]
	v_lshlrev_b32_e32 v159, 7, v184
	s_waitcnt vmcnt(7)
	v_lshlrev_b32_e32 v86, 16, v82
	v_mul_f32_e32 v65, 0xbfb8aa3b, v86
	v_exp_f32_e32 v65, v65
	v_and_b32_e32 v87, 0xffff0000, v82
	v_add_f32_e32 v65, 1.0, v65
	v_rcp_f32_e32 v88, v65
	v_mul_f32_e32 v65, 0xbfb8aa3b, v87
	v_exp_f32_e32 v65, v65
	s_nop 0
	v_add_f32_e32 v65, 1.0, v65
	v_rcp_f32_e32 v89, v65
	s_nop 0
	v_pk_mul_f32 v[86:87], v[88:89], v[86:87]
	s_nop 0
	v_pk_mul_f32 v[48:49], v[86:87], v[48:49]
	s_nop 0
	v_cvt_pk_bf16_f32 v82, v48, v49
	v_lshlrev_b32_e32 v48, 16, v83
	v_mul_f32_e32 v65, 0xbfb8aa3b, v48
	v_exp_f32_e32 v65, v65
	v_and_b32_e32 v49, 0xffff0000, v83
	v_add_f32_e32 v65, 1.0, v65
	v_rcp_f32_e32 v86, v65
	v_mul_f32_e32 v65, 0xbfb8aa3b, v49
	v_exp_f32_e32 v65, v65
	s_nop 0
	v_add_f32_e32 v65, 1.0, v65
	v_rcp_f32_e32 v87, v65
	s_nop 0
	v_pk_mul_f32 v[48:49], v[86:87], v[48:49]
	s_nop 0
	v_pk_mul_f32 v[48:49], v[48:49], v[50:51]
	s_waitcnt vmcnt(6)
	v_lshlrev_b32_e32 v50, 16, v80
	v_mul_f32_e32 v65, 0xbfb8aa3b, v50
	v_exp_f32_e32 v65, v65
	v_cvt_pk_bf16_f32 v83, v48, v49
	v_lshl_add_u64 v[48:49], v[84:85], 0, v[144:145]
	v_and_b32_e32 v51, 0xffff0000, v80
	v_add_f32_e32 v65, 1.0, v65
	v_lshrrev_b32_e32 v236, 2, v252
	v_and_b32_e32 v236, 8, v236
	v_add_u32_e32 v234, v48, v236
	v_mov_b32_e32 v235, v49
	v_mov_b32_e32 v228, v82
	v_mov_b32_e32 v229, v83
	v_rcp_f32_e32 v82, v65
	v_mul_f32_e32 v65, 0xbfb8aa3b, v51
	v_exp_f32_e32 v65, v65
	s_nop 0
	v_add_f32_e32 v65, 1.0, v65
	v_rcp_f32_e32 v83, v65
	v_ashrrev_i32_e32 v65, 31, v64
	v_pk_mul_f32 v[50:51], v[82:83], v[50:51]
	s_nop 0
	v_pk_mul_f32 v[50:51], v[50:51], v[52:53]
	v_lshlrev_b32_e32 v52, 16, v81
	v_cvt_pk_bf16_f32 v50, v50, v51
	v_mul_f32_e32 v51, 0xbfb8aa3b, v52
	v_exp_f32_e32 v51, v51
	v_and_b32_e32 v53, 0xffff0000, v81
	v_add_f32_e32 v51, 1.0, v51
	v_rcp_f32_e32 v80, v51
	v_mul_f32_e32 v51, 0xbfb8aa3b, v53
	v_exp_f32_e32 v51, v51
	s_nop 0
	v_add_f32_e32 v51, 1.0, v51
	v_rcp_f32_e32 v81, v51
	s_nop 0
	v_pk_mul_f32 v[52:53], v[80:81], v[52:53]
	s_nop 0
	v_pk_mul_f32 v[52:53], v[52:53], v[54:55]
	v_pk_mul_f32 v[54:55], v[56:57], v[70:71] op_sel_hi:[1,0]
	v_cvt_pk_bf16_f32 v51, v52, v53
	v_mov_b32_e32 v230, v50
	v_mov_b32_e32 v231, v51
	s_nop 1
	v_permlane32_swap_b32_e32 v228, v230
	v_permlane32_swap_b32_e32 v229, v231
	global_store_dwordx4 v[234:235], v[228:231], off offset:1024
	s_waitcnt vmcnt(6)
	v_lshlrev_b32_e32 v50, 16, v78
	v_and_b32_e32 v51, 0xffff0000, v78
	v_mul_f32_e32 v52, 0xbfb8aa3b, v50
	v_mul_f32_e32 v53, 0xbfb8aa3b, v51
	v_exp_f32_e32 v52, v52
	v_exp_f32_e32 v53, v53
	v_pk_mul_f32 v[56:57], v[58:59], v[70:71] op_sel_hi:[1,0]
	v_add_f32_e32 v52, 1.0, v52
	v_add_f32_e32 v53, 1.0, v53
	v_rcp_f32_e32 v52, v52
	v_rcp_f32_e32 v53, v53
	s_nop 0
	v_pk_mul_f32 v[50:51], v[52:53], v[50:51]
	s_nop 0
	v_pk_mul_f32 v[50:51], v[50:51], v[54:55]
	v_lshlrev_b32_e32 v52, 16, v79
	v_cvt_pk_bf16_f32 v50, v50, v51
	v_mul_f32_e32 v51, 0xbfb8aa3b, v52
	v_exp_f32_e32 v51, v51
	v_and_b32_e32 v53, 0xffff0000, v79
	v_add_f32_e32 v51, 1.0, v51
	v_rcp_f32_e32 v54, v51
	v_mul_f32_e32 v51, 0xbfb8aa3b, v53
	v_exp_f32_e32 v51, v51
	s_nop 0
	v_add_f32_e32 v51, 1.0, v51
	v_rcp_f32_e32 v55, v51
	s_nop 0
	v_pk_mul_f32 v[52:53], v[54:55], v[52:53]
	s_nop 0
	v_pk_mul_f32 v[52:53], v[52:53], v[56:57]
	v_pk_mul_f32 v[54:55], v[60:61], v[70:71] op_sel_hi:[1,0]
	v_cvt_pk_bf16_f32 v51, v52, v53
	v_mov_b32_e32 v228, v50
	v_mov_b32_e32 v229, v51
	s_waitcnt vmcnt(5)
	v_lshlrev_b32_e32 v50, 16, v76
	v_and_b32_e32 v51, 0xffff0000, v76
	v_mul_f32_e32 v52, 0xbfb8aa3b, v50
	v_mul_f32_e32 v53, 0xbfb8aa3b, v51
	v_exp_f32_e32 v52, v52
	v_exp_f32_e32 v53, v53
	v_pk_mul_f32 v[56:57], v[62:63], v[70:71] op_sel_hi:[1,0]
	v_add_f32_e32 v52, 1.0, v52
	v_add_f32_e32 v53, 1.0, v53
	v_rcp_f32_e32 v52, v52
	v_rcp_f32_e32 v53, v53
	s_nop 0
	v_pk_mul_f32 v[50:51], v[52:53], v[50:51]
	s_nop 0
	v_pk_mul_f32 v[50:51], v[50:51], v[54:55]
	v_lshlrev_b32_e32 v52, 16, v77
	v_cvt_pk_bf16_f32 v50, v50, v51
	v_mul_f32_e32 v51, 0xbfb8aa3b, v52
	v_exp_f32_e32 v51, v51
	v_and_b32_e32 v53, 0xffff0000, v77
	v_add_f32_e32 v51, 1.0, v51
	v_rcp_f32_e32 v54, v51
	v_mul_f32_e32 v51, 0xbfb8aa3b, v53
	v_exp_f32_e32 v51, v51
	s_nop 0
	v_add_f32_e32 v51, 1.0, v51
	v_rcp_f32_e32 v55, v51
	s_nop 0
	v_pk_mul_f32 v[52:53], v[54:55], v[52:53]
	s_nop 0
	v_pk_mul_f32 v[52:53], v[52:53], v[56:57]
	s_nop 0
	v_cvt_pk_bf16_f32 v51, v52, v53
	v_mov_b32_e32 v230, v50
	v_mov_b32_e32 v231, v51
	s_nop 1
	v_permlane32_swap_b32_e32 v228, v230
	v_permlane32_swap_b32_e32 v229, v231
	global_store_dwordx4 v[234:235], v[228:231], off offset:1056
	s_waitcnt vmcnt(5)
; __device__ __forceinline__ unsigned cvt_pk_bf16(float lo, float hi) { f32x2_c v = {lo, hi}; bf16x2_c b = __builtin_convertvector(v, bf16x2_c); return __builtin_bit_cast(unsigned, b); }
; __device__ __forceinline__ float silu_f(float z) { return z * __builtin_amdgcn_rcpf(1.f + __expf(-z)); }
; __device__ __forceinline__ void la_loadz(u32x2 (&z)[8], const bf16_t* zrow, int hi) {
; #pragma unroll
;     for (int db = 0; db < 2; ++db)
; #pragma unroll
;         for (int g = 0; g < 4; ++g) z[4 * db + g] = *(const u32x2*)(zrow + 32 * db + 8 * g + 4 * hi);
; }
; __device__ __forceinline__ void la_store(const LA& st, bool use_sink, float sink2, const u32x2 (&zv)[8], bf16_t* yrow, int hi) {
;     float l = st.l; { auto rr = __builtin_amdgcn_permlane32_swap(__float_as_uint(l), __float_as_uint(l), false, false); l = __uint_as_float(rr[0]) + __uint_as_float(rr[1]); }
;     float inv;
;     if (use_sink) { const float m2 = fmaxf(st.m, sink2), a = __builtin_amdgcn_exp2f(st.m - m2); inv = a * __builtin_amdgcn_rcpf(l * a + __builtin_amdgcn_exp2f(sink2 - m2)); }
;     else inv = __builtin_amdgcn_rcpf(l);
; #pragma unroll
;     for (int db = 0; db < 2; ++db)
; #pragma unroll
;         for (int g = 0; g < 4; ++g) { const int c = 32 * db + 8 * g + 4 * hi; const u32x2 z = zv[4 * db + g];
;             const f32x16& o = db ? st.o1 : st.o0;
;             u32x2 w; w.x = cvt_pk_bf16(o[4 * g] * inv * silu_f(bf_lo(z.x)), o[4 * g + 1] * inv * silu_f(bf_hi(z.x)));
;             w.y = cvt_pk_bf16(o[4 * g + 2] * inv * silu_f(bf_lo(z.y)), o[4 * g + 3] * inv * silu_f(bf_hi(z.y)));
;             *(u32x2*)(yrow + c) = w; }
; __global__ void __launch_bounds__(NWAVES * 64, 2) mk_fwd(Args args) {
;     ...
;                 u32x2 zv[8];
;                 la_loadz(zv, PROJ + (size_t)tqa * PP + C_ZB + h * 64, hi); la_store(sa, false, 0.f, zv, Yb + (size_t)tqa * DMODEL + 512 + h * 64, hi);
;                 la_loadz(zv, PROJ + (size_t)tqb * PP + C_ZB + h * 64, hi); la_store(sb, false, 0.f, zv, Yb + (size_t)tqb * DMODEL + 512 + h * 64, hi);
	v_lshlrev_b32_e32 v50, 16, v74
	v_and_b32_e32 v51, 0xffff0000, v74
	v_mul_f32_e32 v52, 0xbfb8aa3b, v50
	v_mul_f32_e32 v53, 0xbfb8aa3b, v51
	v_exp_f32_e32 v52, v52
	v_exp_f32_e32 v53, v53
	v_add_f32_e32 v52, 1.0, v52
	v_add_f32_e32 v53, 1.0, v53
	v_rcp_f32_e32 v52, v52
	v_rcp_f32_e32 v53, v53
	s_nop 0
	v_pk_mul_f32 v[50:51], v[52:53], v[50:51]
	s_nop 0
	v_pk_mul_f32 v[32:33], v[50:51], v[32:33]
	v_lshlrev_b32_e32 v50, 16, v75
	v_cvt_pk_bf16_f32 v32, v32, v33
	v_mul_f32_e32 v33, 0xbfb8aa3b, v50
	v_exp_f32_e32 v33, v33
	v_and_b32_e32 v51, 0xffff0000, v75
	v_add_f32_e32 v33, 1.0, v33
	v_rcp_f32_e32 v52, v33
	v_mul_f32_e32 v33, 0xbfb8aa3b, v51
	v_exp_f32_e32 v33, v33
	s_nop 0
	v_add_f32_e32 v33, 1.0, v33
	v_rcp_f32_e32 v53, v33
	s_nop 0
	v_pk_mul_f32 v[50:51], v[52:53], v[50:51]
	s_nop 0
	v_pk_mul_f32 v[34:35], v[50:51], v[34:35]
	s_nop 0
	v_cvt_pk_bf16_f32 v33, v34, v35
	v_mov_b32_e32 v228, v32
	v_mov_b32_e32 v229, v33
	s_waitcnt vmcnt(4)
	v_lshlrev_b32_e32 v32, 16, v72
	v_and_b32_e32 v33, 0xffff0000, v72
	v_mul_f32_e32 v34, 0xbfb8aa3b, v32
	v_mul_f32_e32 v35, 0xbfb8aa3b, v33
	v_exp_f32_e32 v34, v34
	v_exp_f32_e32 v35, v35
	v_add_f32_e32 v34, 1.0, v34
	v_add_f32_e32 v35, 1.0, v35
	v_rcp_f32_e32 v34, v34
	v_rcp_f32_e32 v35, v35
	s_nop 0
	v_pk_mul_f32 v[32:33], v[34:35], v[32:33]
	s_nop 0
	v_pk_mul_f32 v[32:33], v[36:37], v[32:33]
	v_lshlrev_b32_e32 v34, 16, v73
	v_cvt_pk_bf16_f32 v32, v32, v33
	v_mul_f32_e32 v33, 0xbfb8aa3b, v34
	v_exp_f32_e32 v33, v33
	v_and_b32_e32 v35, 0xffff0000, v73
	v_add_f32_e32 v33, 1.0, v33
	v_rcp_f32_e32 v36, v33
	v_mul_f32_e32 v33, 0xbfb8aa3b, v35
	v_exp_f32_e32 v33, v33
	s_nop 0
	v_add_f32_e32 v33, 1.0, v33
	v_rcp_f32_e32 v37, v33
	s_nop 0
	v_pk_mul_f32 v[34:35], v[36:37], v[34:35]
	s_nop 0
	v_pk_mul_f32 v[34:35], v[38:39], v[34:35]
	v_pk_mul_f32 v[36:37], v[40:41], v[70:71] op_sel_hi:[1,0]
	v_cvt_pk_bf16_f32 v33, v34, v35
	v_mov_b32_e32 v230, v32
	v_mov_b32_e32 v231, v33
	s_nop 1
	v_permlane32_swap_b32_e32 v228, v230
	v_permlane32_swap_b32_e32 v229, v231
	global_store_dwordx4 v[234:235], v[228:231], off offset:1088
	s_waitcnt vmcnt(4)
	v_lshlrev_b32_e32 v32, 16, v68
	v_and_b32_e32 v33, 0xffff0000, v68
	v_mul_f32_e32 v34, 0xbfb8aa3b, v32
	v_mul_f32_e32 v35, 0xbfb8aa3b, v33
	v_exp_f32_e32 v34, v34
	v_exp_f32_e32 v35, v35
	v_pk_mul_f32 v[38:39], v[42:43], v[70:71] op_sel_hi:[1,0]
	v_add_f32_e32 v34, 1.0, v34
	v_add_f32_e32 v35, 1.0, v35
	v_rcp_f32_e32 v34, v34
	v_rcp_f32_e32 v35, v35
	s_nop 0
	v_pk_mul_f32 v[32:33], v[34:35], v[32:33]
	s_nop 0
	v_pk_mul_f32 v[32:33], v[36:37], v[32:33]
	v_lshlrev_b32_e32 v34, 16, v69
	v_cvt_pk_bf16_f32 v32, v32, v33
	v_mul_f32_e32 v33, 0xbfb8aa3b, v34
	v_exp_f32_e32 v33, v33
	v_and_b32_e32 v35, 0xffff0000, v69
	v_add_f32_e32 v33, 1.0, v33
	v_rcp_f32_e32 v36, v33
	v_mul_f32_e32 v33, 0xbfb8aa3b, v35
	v_exp_f32_e32 v33, v33
	s_nop 0
	v_add_f32_e32 v33, 1.0, v33
	v_rcp_f32_e32 v37, v33
	s_nop 0
	v_pk_mul_f32 v[34:35], v[36:37], v[34:35]
	s_nop 0
	v_pk_mul_f32 v[34:35], v[38:39], v[34:35]
	v_pk_mul_f32 v[36:37], v[44:45], v[70:71] op_sel_hi:[1,0]
	v_cvt_pk_bf16_f32 v33, v34, v35
	v_mov_b32_e32 v228, v32
	v_mov_b32_e32 v229, v33
	s_waitcnt vmcnt(3)
	v_lshlrev_b32_e32 v32, 16, v66
	v_and_b32_e32 v33, 0xffff0000, v66
	v_mul_f32_e32 v34, 0xbfb8aa3b, v32
	v_mul_f32_e32 v35, 0xbfb8aa3b, v33
	v_exp_f32_e32 v34, v34
	v_exp_f32_e32 v35, v35
	v_pk_mul_f32 v[38:39], v[46:47], v[70:71] op_sel_hi:[1,0]
	v_add_f32_e32 v34, 1.0, v34
	v_add_f32_e32 v35, 1.0, v35
	v_rcp_f32_e32 v34, v34
	v_rcp_f32_e32 v35, v35
	s_nop 0
	v_pk_mul_f32 v[32:33], v[34:35], v[32:33]
	s_nop 0
	v_pk_mul_f32 v[32:33], v[36:37], v[32:33]
	v_lshlrev_b32_e32 v34, 16, v67
	v_cvt_pk_bf16_f32 v32, v32, v33
	v_mul_f32_e32 v33, 0xbfb8aa3b, v34
	v_exp_f32_e32 v33, v33
	v_and_b32_e32 v35, 0xffff0000, v67
	v_add_f32_e32 v33, 1.0, v33
	v_rcp_f32_e32 v36, v33
	v_mul_f32_e32 v33, 0xbfb8aa3b, v35
	v_exp_f32_e32 v33, v33
	s_nop 0
	v_add_f32_e32 v33, 1.0, v33
	v_rcp_f32_e32 v37, v33
	s_nop 0
	v_pk_mul_f32 v[34:35], v[36:37], v[34:35]
	s_nop 0
	v_pk_mul_f32 v[34:35], v[38:39], v[34:35]
	s_nop 0
	v_cvt_pk_bf16_f32 v33, v34, v35
	v_mov_b32_e32 v230, v32
	v_mov_b32_e32 v231, v33
	s_nop 1
	v_permlane32_swap_b32_e32 v228, v230
	v_permlane32_swap_b32_e32 v229, v231
	global_store_dwordx4 v[234:235], v[228:231], off offset:1120
	v_mov_b64_e32 v[32:33], s[74:75]
	v_mad_i64_i32 v[34:35], s[6:7], v64, s64, v[32:33]
	v_lshl_add_u64 v[34:35], v[34:35], 0, s[70:71]
	v_lshl_add_u64 v[36:37], v[34:35], 0, v[144:145]
	v_lshl_add_u64 v[34:35], v[36:37], 0, s[8:9]
	v_add_co_u32_e32 v36, vcc, s0, v36
	s_ashr_i32 s6, s58, 5
	s_nop 0
	v_addc_co_u32_e32 v37, vcc, 0, v37, vcc
	global_load_dwordx2 v[50:51], v[36:37], off offset:1536
	global_load_dwordx2 v[48:49], v[34:35], off offset:16
	global_load_dwordx2 v[46:47], v[34:35], off offset:32
	global_load_dwordx2 v[44:45], v[34:35], off offset:48
	global_load_dwordx2 v[42:43], v[34:35], off offset:64
	global_load_dwordx2 v[40:41], v[34:35], off offset:80
	global_load_dwordx2 v[38:39], v[34:35], off offset:96
	s_nop 0
	global_load_dwordx2 v[34:35], v[34:35], off offset:112
	v_lshlrev_b64 v[36:37], 12, v[64:65]
	v_lshl_add_u64 v[36:37], s[42:43], 0, v[36:37]
	v_lshl_add_u64 v[52:53], v[36:37], 0, s[70:71]
	v_mov_b32_e32 v36, v156
	s_nop 1
	v_permlane32_swap_b32_e32 v156, v36
	v_add_f32_e32 v36, v156, v36
	v_rcp_f32_e32 v36, v36
	s_bfe_u32 s0, s58, 0x20006
	s_and_b32 s6, s6, -8
	s_or_b32 s8, s0, s6
	v_cndmask_b32_e64 v156, 0, 1.0, s[4:5]
	s_add_i32 s4, 0, 0x19000
	v_add_u32_e32 v112, s8, v157
	v_readlane_b32 s58, v255, 30
	v_readlane_b32 s59, v255, 31
	v_mov_b32_e32 v158, v156
	s_movk_i32 s59, 0xffe0
	s_waitcnt vmcnt(7)
; __device__ __forceinline__ unsigned cvt_pk_bf16(float lo, float hi) { f32x2_c v = {lo, hi}; bf16x2_c b = __builtin_convertvector(v, bf16x2_c); return __builtin_bit_cast(unsigned, b); }
; __device__ __forceinline__ float silu_f(float z) { return z * __builtin_amdgcn_rcpf(1.f + __expf(-z)); }
; __device__ __forceinline__ void la_store(const LA& st, bool use_sink, float sink2, const u32x2 (&zv)[8], bf16_t* yrow, int hi) {
;     float l = st.l; { auto rr = __builtin_amdgcn_permlane32_swap(__float_as_uint(l), __float_as_uint(l), false, false); l = __uint_as_float(rr[0]) + __uint_as_float(rr[1]); }
;     float inv;
;     if (use_sink) { const float m2 = fmaxf(st.m, sink2), a = __builtin_amdgcn_exp2f(st.m - m2); inv = a * __builtin_amdgcn_rcpf(l * a + __builtin_amdgcn_exp2f(sink2 - m2)); }
;     else inv = __builtin_amdgcn_rcpf(l);
; #pragma unroll
;     for (int db = 0; db < 2; ++db)
; #pragma unroll
;         for (int g = 0; g < 4; ++g) { const int c = 32 * db + 8 * g + 4 * hi; const u32x2 z = zv[4 * db + g];
;             const f32x16& o = db ? st.o1 : st.o0;
;             u32x2 w; w.x = cvt_pk_bf16(o[4 * g] * inv * silu_f(bf_lo(z.x)), o[4 * g + 1] * inv * silu_f(bf_hi(z.x)));
;             w.y = cvt_pk_bf16(o[4 * g + 2] * inv * silu_f(bf_lo(z.y)), o[4 * g + 3] * inv * silu_f(bf_hi(z.y)));
;             *(u32x2*)(yrow + c) = w; }
; __global__ void __launch_bounds__(NWAVES * 64, 2) mk_fwd(Args args) {
;     ...
;                 la_loadz(zv, PROJ + (size_t)tqb * PP + C_ZB + h * 64, hi); la_store(sb, false, 0.f, zv, Yb + (size_t)tqb * DMODEL + 512 + h * 64, hi);
	v_lshlrev_b32_e32 v54, 16, v50
	v_mul_f32_e32 v37, 0xbfb8aa3b, v54
	v_exp_f32_e32 v37, v37
	v_and_b32_e32 v55, 0xffff0000, v50
	v_add_f32_e32 v37, 1.0, v37
	v_rcp_f32_e32 v56, v37
	v_pk_mul_f32 v[16:17], v[16:17], v[36:37] op_sel_hi:[1,0]
	v_mul_f32_e32 v37, 0xbfb8aa3b, v55
	v_exp_f32_e32 v37, v37
	s_nop 0
	v_add_f32_e32 v37, 1.0, v37
	v_rcp_f32_e32 v57, v37
	s_nop 0
	v_pk_mul_f32 v[54:55], v[56:57], v[54:55]
	s_nop 0
	v_pk_mul_f32 v[16:17], v[54:55], v[16:17]
	s_nop 0
	v_cvt_pk_bf16_f32 v50, v16, v17
	v_lshlrev_b32_e32 v16, 16, v51
	v_mul_f32_e32 v37, 0xbfb8aa3b, v16
	v_exp_f32_e32 v37, v37
	v_and_b32_e32 v17, 0xffff0000, v51
	v_add_f32_e32 v37, 1.0, v37
	v_rcp_f32_e32 v54, v37
	v_pk_mul_f32 v[18:19], v[18:19], v[36:37] op_sel_hi:[1,0]
	v_mul_f32_e32 v37, 0xbfb8aa3b, v17
	v_exp_f32_e32 v37, v37
	s_nop 0
	v_add_f32_e32 v37, 1.0, v37
	v_rcp_f32_e32 v55, v37
	s_nop 0
	v_pk_mul_f32 v[16:17], v[54:55], v[16:17]
	s_nop 0
	v_pk_mul_f32 v[16:17], v[16:17], v[18:19]
	s_waitcnt vmcnt(6)
	v_lshlrev_b32_e32 v18, 16, v48
	v_mul_f32_e32 v37, 0xbfb8aa3b, v18
	v_exp_f32_e32 v37, v37
	v_cvt_pk_bf16_f32 v51, v16, v17
	v_lshl_add_u64 v[16:17], v[52:53], 0, v[144:145]
	v_and_b32_e32 v19, 0xffff0000, v48
	v_add_f32_e32 v37, 1.0, v37
	v_lshrrev_b32_e32 v236, 2, v252
	v_and_b32_e32 v236, 8, v236
	v_add_u32_e32 v234, v16, v236
	v_mov_b32_e32 v235, v17
	v_mov_b32_e32 v228, v50
	v_mov_b32_e32 v229, v51
	v_rcp_f32_e32 v50, v37
	v_pk_mul_f32 v[20:21], v[20:21], v[36:37] op_sel_hi:[1,0]
	v_mul_f32_e32 v37, 0xbfb8aa3b, v19
	v_exp_f32_e32 v37, v37
	s_nop 0
	v_add_f32_e32 v37, 1.0, v37
	v_rcp_f32_e32 v51, v37
	v_pk_mul_f32 v[22:23], v[22:23], v[36:37] op_sel_hi:[1,0]
	v_pk_mul_f32 v[0:1], v[0:1], v[36:37] op_sel_hi:[1,0]
	v_pk_mul_f32 v[2:3], v[2:3], v[36:37] op_sel_hi:[1,0]
	v_pk_mul_f32 v[18:19], v[50:51], v[18:19]
	v_pk_mul_f32 v[4:5], v[4:5], v[36:37] op_sel_hi:[1,0]
	v_pk_mul_f32 v[18:19], v[18:19], v[20:21]
	v_lshlrev_b32_e32 v20, 16, v49
	v_cvt_pk_bf16_f32 v18, v18, v19
	v_mul_f32_e32 v19, 0xbfb8aa3b, v20
	v_exp_f32_e32 v19, v19
	v_and_b32_e32 v21, 0xffff0000, v49
	v_pk_mul_f32 v[6:7], v[6:7], v[36:37] op_sel_hi:[1,0]
	v_add_f32_e32 v19, 1.0, v19
	v_rcp_f32_e32 v48, v19
	v_mul_f32_e32 v19, 0xbfb8aa3b, v21
	v_exp_f32_e32 v19, v19
	s_nop 0
	v_add_f32_e32 v19, 1.0, v19
	v_rcp_f32_e32 v49, v19
	s_nop 0
	v_pk_mul_f32 v[20:21], v[48:49], v[20:21]
	s_nop 0
	v_pk_mul_f32 v[20:21], v[20:21], v[22:23]
	v_pk_mul_f32 v[22:23], v[24:25], v[36:37] op_sel_hi:[1,0]
	v_cvt_pk_bf16_f32 v19, v20, v21
	v_mov_b32_e32 v230, v18
	v_mov_b32_e32 v231, v19
	s_nop 1
	v_permlane32_swap_b32_e32 v228, v230
	v_permlane32_swap_b32_e32 v229, v231
	global_store_dwordx4 v[234:235], v[228:231], off offset:1024
	s_waitcnt vmcnt(6)
	v_lshlrev_b32_e32 v18, 16, v46
	v_and_b32_e32 v19, 0xffff0000, v46
	v_mul_f32_e32 v20, 0xbfb8aa3b, v18
	v_mul_f32_e32 v21, 0xbfb8aa3b, v19
	v_exp_f32_e32 v20, v20
	v_exp_f32_e32 v21, v21
	v_pk_mul_f32 v[24:25], v[26:27], v[36:37] op_sel_hi:[1,0]
	v_add_f32_e32 v20, 1.0, v20
	v_add_f32_e32 v21, 1.0, v21
	v_rcp_f32_e32 v20, v20
	v_rcp_f32_e32 v21, v21
	s_nop 0
	v_pk_mul_f32 v[18:19], v[20:21], v[18:19]
	s_nop 0
	v_pk_mul_f32 v[18:19], v[18:19], v[22:23]
	v_lshlrev_b32_e32 v20, 16, v47
	v_cvt_pk_bf16_f32 v18, v18, v19
	v_mul_f32_e32 v19, 0xbfb8aa3b, v20
	v_exp_f32_e32 v19, v19
	v_and_b32_e32 v21, 0xffff0000, v47
	v_add_f32_e32 v19, 1.0, v19
	v_rcp_f32_e32 v22, v19
	v_mul_f32_e32 v19, 0xbfb8aa3b, v21
	v_exp_f32_e32 v19, v19
	s_nop 0
	v_add_f32_e32 v19, 1.0, v19
	v_rcp_f32_e32 v23, v19
	s_nop 0
	v_pk_mul_f32 v[20:21], v[22:23], v[20:21]
	s_nop 0
	v_pk_mul_f32 v[20:21], v[20:21], v[24:25]
	v_pk_mul_f32 v[22:23], v[28:29], v[36:37] op_sel_hi:[1,0]
	v_cvt_pk_bf16_f32 v19, v20, v21
	v_mov_b32_e32 v228, v18
	v_mov_b32_e32 v229, v19
	s_waitcnt vmcnt(5)
	v_lshlrev_b32_e32 v18, 16, v44
	v_and_b32_e32 v19, 0xffff0000, v44
	v_mul_f32_e32 v20, 0xbfb8aa3b, v18
	v_mul_f32_e32 v21, 0xbfb8aa3b, v19
	v_exp_f32_e32 v20, v20
	v_exp_f32_e32 v21, v21
	v_pk_mul_f32 v[24:25], v[30:31], v[36:37] op_sel_hi:[1,0]
	v_add_f32_e32 v20, 1.0, v20
	v_add_f32_e32 v21, 1.0, v21
	v_rcp_f32_e32 v20, v20
	v_rcp_f32_e32 v21, v21
	s_nop 0
	v_pk_mul_f32 v[18:19], v[20:21], v[18:19]
	s_nop 0
	v_pk_mul_f32 v[18:19], v[18:19], v[22:23]
	v_lshlrev_b32_e32 v20, 16, v45
	v_cvt_pk_bf16_f32 v18, v18, v19
	v_mul_f32_e32 v19, 0xbfb8aa3b, v20
	v_exp_f32_e32 v19, v19
	v_and_b32_e32 v21, 0xffff0000, v45
	v_add_f32_e32 v19, 1.0, v19
	v_rcp_f32_e32 v22, v19
	v_mul_f32_e32 v19, 0xbfb8aa3b, v21
	v_exp_f32_e32 v19, v19
	s_nop 0
	v_add_f32_e32 v19, 1.0, v19
	v_rcp_f32_e32 v23, v19
	s_nop 0
	v_pk_mul_f32 v[20:21], v[22:23], v[20:21]
	s_nop 0
	v_pk_mul_f32 v[20:21], v[20:21], v[24:25]
	s_nop 0
	v_cvt_pk_bf16_f32 v19, v20, v21
	v_mov_b32_e32 v230, v18
	v_mov_b32_e32 v231, v19
	s_nop 1
	v_permlane32_swap_b32_e32 v228, v230
	v_permlane32_swap_b32_e32 v229, v231
	global_store_dwordx4 v[234:235], v[228:231], off offset:1056
	s_waitcnt vmcnt(5)
	v_lshlrev_b32_e32 v18, 16, v42
	v_and_b32_e32 v19, 0xffff0000, v42
	v_mul_f32_e32 v20, 0xbfb8aa3b, v18
	v_mul_f32_e32 v21, 0xbfb8aa3b, v19
	v_exp_f32_e32 v20, v20
	v_exp_f32_e32 v21, v21
	v_add_f32_e32 v20, 1.0, v20
	v_add_f32_e32 v21, 1.0, v21
	v_rcp_f32_e32 v20, v20
	v_rcp_f32_e32 v21, v21
	s_nop 0
	v_pk_mul_f32 v[18:19], v[20:21], v[18:19]
	s_nop 0
	v_pk_mul_f32 v[0:1], v[18:19], v[0:1]
	v_lshlrev_b32_e32 v18, 16, v43
	v_cvt_pk_bf16_f32 v0, v0, v1
	v_mul_f32_e32 v1, 0xbfb8aa3b, v18
	v_exp_f32_e32 v1, v1
	v_and_b32_e32 v19, 0xffff0000, v43
	v_add_f32_e32 v1, 1.0, v1
	v_rcp_f32_e32 v20, v1
	v_mul_f32_e32 v1, 0xbfb8aa3b, v19
	v_exp_f32_e32 v1, v1
	s_nop 0
	v_add_f32_e32 v1, 1.0, v1
	v_rcp_f32_e32 v21, v1
	s_nop 0
	v_pk_mul_f32 v[18:19], v[20:21], v[18:19]
	s_nop 0
	v_pk_mul_f32 v[2:3], v[18:19], v[2:3]
	s_nop 0
	v_cvt_pk_bf16_f32 v1, v2, v3
	v_mov_b32_e32 v228, v0
	v_mov_b32_e32 v229, v1
	s_waitcnt vmcnt(4)
; __device__ __forceinline__ unsigned cvt_pk_bf16(float lo, float hi) { f32x2_c v = {lo, hi}; bf16x2_c b = __builtin_convertvector(v, bf16x2_c); return __builtin_bit_cast(unsigned, b); }
; __device__ __forceinline__ float silu_f(float z) { return z * __builtin_amdgcn_rcpf(1.f + __expf(-z)); }
; __device__ __forceinline__ void la_store(const LA& st, bool use_sink, float sink2, const u32x2 (&zv)[8], bf16_t* yrow, int hi) {
;     float l = st.l; { auto rr = __builtin_amdgcn_permlane32_swap(__float_as_uint(l), __float_as_uint(l), false, false); l = __uint_as_float(rr[0]) + __uint_as_float(rr[1]); }
;     float inv;
;     if (use_sink) { const float m2 = fmaxf(st.m, sink2), a = __builtin_amdgcn_exp2f(st.m - m2); inv = a * __builtin_amdgcn_rcpf(l * a + __builtin_amdgcn_exp2f(sink2 - m2)); }
;     else inv = __builtin_amdgcn_rcpf(l);
; #pragma unroll
;     for (int db = 0; db < 2; ++db)
; #pragma unroll
;         for (int g = 0; g < 4; ++g) { const int c = 32 * db + 8 * g + 4 * hi; const u32x2 z = zv[4 * db + g];
;             const f32x16& o = db ? st.o1 : st.o0;
;             u32x2 w; w.x = cvt_pk_bf16(o[4 * g] * inv * silu_f(bf_lo(z.x)), o[4 * g + 1] * inv * silu_f(bf_hi(z.x)));
;             w.y = cvt_pk_bf16(o[4 * g + 2] * inv * silu_f(bf_lo(z.y)), o[4 * g + 3] * inv * silu_f(bf_hi(z.y)));
;             *(u32x2*)(yrow + c) = w; }
; __global__ void __launch_bounds__(NWAVES * 64, 2) mk_fwd(Args args) {
;     ...
;                 la_loadz(zv, PROJ + (size_t)tqb * PP + C_ZB + h * 64, hi); la_store(sb, false, 0.f, zv, Yb + (size_t)tqb * DMODEL + 512 + h * 64, hi);
;             }
;             __syncthreads();
;             {
;                 const int cA = (wave & 3) + 8 * (wave >> 2), cB = cA + 4, s0 = 32 * v32, tqa = 16 * (s0 + r32) + cA, tqb = tqa + 4;
;                 bf16x8 qa[4], qb[4]; const bf16_t* qp = PROJ + (size_t)tqa * PP + C_QD + h * 64 + 8 * hi;
; #pragma unroll
;                 for (int d0 = 0; d0 < 4; ++d0) { qa[d0] = *(const bf16x8*)(qp + 16 * d0); qb[d0] = *(const bf16x8*)(qp + (size_t)4 * PP + 16 * d0); }
	v_lshlrev_b32_e32 v0, 16, v40
	v_and_b32_e32 v1, 0xffff0000, v40
	v_mul_f32_e32 v2, 0xbfb8aa3b, v0
	v_mul_f32_e32 v3, 0xbfb8aa3b, v1
	v_exp_f32_e32 v2, v2
	v_exp_f32_e32 v3, v3
	v_add_f32_e32 v2, 1.0, v2
	v_add_f32_e32 v3, 1.0, v3
	v_rcp_f32_e32 v2, v2
	v_rcp_f32_e32 v3, v3
	s_nop 0
	v_pk_mul_f32 v[0:1], v[2:3], v[0:1]
	s_nop 0
	v_pk_mul_f32 v[0:1], v[4:5], v[0:1]
	v_lshlrev_b32_e32 v2, 16, v41
	v_cvt_pk_bf16_f32 v0, v0, v1
	v_mul_f32_e32 v1, 0xbfb8aa3b, v2
	v_exp_f32_e32 v1, v1
	v_and_b32_e32 v3, 0xffff0000, v41
	v_add_f32_e32 v1, 1.0, v1
	v_rcp_f32_e32 v4, v1
	v_mul_f32_e32 v1, 0xbfb8aa3b, v3
	v_exp_f32_e32 v1, v1
	s_nop 0
	v_add_f32_e32 v1, 1.0, v1
	v_rcp_f32_e32 v5, v1
	s_nop 0
	v_pk_mul_f32 v[2:3], v[4:5], v[2:3]
	s_nop 0
	v_pk_mul_f32 v[2:3], v[6:7], v[2:3]
	v_pk_mul_f32 v[4:5], v[8:9], v[36:37] op_sel_hi:[1,0]
	v_cvt_pk_bf16_f32 v1, v2, v3
	v_mov_b32_e32 v230, v0
	v_mov_b32_e32 v231, v1
	s_nop 1
	v_permlane32_swap_b32_e32 v228, v230
	v_permlane32_swap_b32_e32 v229, v231
	global_store_dwordx4 v[234:235], v[228:231], off offset:1088
	s_waitcnt vmcnt(4)
	v_lshlrev_b32_e32 v0, 16, v38
	v_and_b32_e32 v1, 0xffff0000, v38
	v_mul_f32_e32 v2, 0xbfb8aa3b, v0
	v_mul_f32_e32 v3, 0xbfb8aa3b, v1
	v_exp_f32_e32 v2, v2
	v_exp_f32_e32 v3, v3
	v_pk_mul_f32 v[6:7], v[10:11], v[36:37] op_sel_hi:[1,0]
	v_add_f32_e32 v2, 1.0, v2
	v_add_f32_e32 v3, 1.0, v3
	v_rcp_f32_e32 v2, v2
	v_rcp_f32_e32 v3, v3
	s_nop 0
	v_pk_mul_f32 v[0:1], v[2:3], v[0:1]
	s_nop 0
	v_pk_mul_f32 v[0:1], v[4:5], v[0:1]
	v_lshlrev_b32_e32 v2, 16, v39
	v_cvt_pk_bf16_f32 v0, v0, v1
	v_mul_f32_e32 v1, 0xbfb8aa3b, v2
	v_exp_f32_e32 v1, v1
	v_and_b32_e32 v3, 0xffff0000, v39
	v_add_f32_e32 v1, 1.0, v1
	v_rcp_f32_e32 v4, v1
	v_mul_f32_e32 v1, 0xbfb8aa3b, v3
	v_exp_f32_e32 v1, v1
	s_nop 0
	v_add_f32_e32 v1, 1.0, v1
	v_rcp_f32_e32 v5, v1
	s_nop 0
	v_pk_mul_f32 v[2:3], v[4:5], v[2:3]
	s_nop 0
	v_pk_mul_f32 v[2:3], v[6:7], v[2:3]
	v_pk_mul_f32 v[4:5], v[12:13], v[36:37] op_sel_hi:[1,0]
	v_cvt_pk_bf16_f32 v1, v2, v3
	v_mov_b32_e32 v228, v0
	v_mov_b32_e32 v229, v1
	s_waitcnt vmcnt(3)
	v_lshlrev_b32_e32 v0, 16, v34
	v_and_b32_e32 v1, 0xffff0000, v34
	v_mul_f32_e32 v2, 0xbfb8aa3b, v0
	v_mul_f32_e32 v3, 0xbfb8aa3b, v1
	v_exp_f32_e32 v2, v2
	v_exp_f32_e32 v3, v3
	v_pk_mul_f32 v[6:7], v[14:15], v[36:37] op_sel_hi:[1,0]
	v_add_f32_e32 v2, 1.0, v2
	v_add_f32_e32 v3, 1.0, v3
	v_rcp_f32_e32 v2, v2
	v_rcp_f32_e32 v3, v3
	s_nop 0
	v_pk_mul_f32 v[0:1], v[2:3], v[0:1]
	s_nop 0
	v_pk_mul_f32 v[0:1], v[4:5], v[0:1]
	v_lshlrev_b32_e32 v2, 16, v35
	v_cvt_pk_bf16_f32 v0, v0, v1
	v_mul_f32_e32 v1, 0xbfb8aa3b, v2
	v_exp_f32_e32 v1, v1
	v_and_b32_e32 v3, 0xffff0000, v35
	v_add_f32_e32 v1, 1.0, v1
	v_rcp_f32_e32 v4, v1
	v_mul_f32_e32 v1, 0xbfb8aa3b, v3
	v_exp_f32_e32 v1, v1
	s_nop 0
	v_add_f32_e32 v1, 1.0, v1
	v_rcp_f32_e32 v5, v1
	s_nop 0
	v_pk_mul_f32 v[2:3], v[4:5], v[2:3]
	s_nop 0
	v_pk_mul_f32 v[2:3], v[6:7], v[2:3]
	s_nop 0
	v_cvt_pk_bf16_f32 v1, v2, v3
	v_mov_b32_e32 v230, v0
	v_mov_b32_e32 v231, v1
	s_nop 1
	v_permlane32_swap_b32_e32 v228, v230
	v_permlane32_swap_b32_e32 v229, v231
	global_store_dwordx4 v[234:235], v[228:231], off offset:1120
	v_or_b32_e32 v0, s1, v186
	v_lshlrev_b32_e32 v0, 4, v0
	v_add_u32_e32 v150, s8, v0
	v_mad_i64_i32 v[2:3], s[6:7], v150, s64, v[32:33]
	v_lshl_add_u64 v[152:153], v[2:3], 0, s[70:71]
	v_lshl_add_u64 v[2:3], v[152:153], 0, v[188:189]
	s_mov_b64 s[6:7], 0x2400
	v_lshl_add_u64 v[4:5], v[2:3], 0, s[6:7]
	s_movk_i32 s6, 0x2000
	v_add_co_u32_e32 v6, vcc, s6, v2
	s_mov_b32 s6, 0xf000
	s_nop 0
	v_addc_co_u32_e32 v7, vcc, 0, v3, vcc
	v_add_co_u32_e32 v2, vcc, s6, v2
	v_lshlrev_b32_e32 v1, 4, v186
	s_nop 0
	v_addc_co_u32_e32 v3, vcc, 0, v3, vcc
	s_barrier
; #define LAS __attribute__((address_space(3)))
; __host__ __device__ __forceinline__ int vt_off(int d, int p) { return (d >> 1) * VTPP + (p >> 5) * 64 + (d & 1) * 32 + (p & 31); }
; __global__ void __launch_bounds__(NWAVES * 64, 2) mk_fwd(Args args) {
;     ...
;                 const int cA = (wave & 3) + 8 * (wave >> 2), cB = cA + 4, s0 = 32 * v32, tqa = 16 * (s0 + r32) + cA, tqb = tqa + 4;
;                 bf16x8 qa[4], qb[4]; const bf16_t* qp = PROJ + (size_t)tqa * PP + C_QD + h * 64 + 8 * hi;
; #pragma unroll
;                 for (int d0 = 0; d0 < 4; ++d0) { qa[d0] = *(const bf16x8*)(qp + 16 * d0); qb[d0] = *(const bf16x8*)(qp + (size_t)4 * PP + 16 * d0); }
;                 LA sa, sb;
; #pragma unroll
;                 for (int w2 = 0; w2 < 2; ++w2) { LA& st = w2 ? sb : sa; const int rho = 16 * r32 + (w2 ? cB : cA);
;                     st.m = LSE1[rho]; st.l = hi ? 0.f : 1.f;
; #pragma unroll
;                     for (int db = 0; db < 2; ++db)
; #pragma unroll
;                         for (int g = 0; g < 4; ++g) { const u32x2 w = *(const LAS u32x2*)(O1 + o1_off(rho, 8 * db + 2 * g + hi));
;                             if (db) { st.o1[4 * g] = bf_lo(w.x); st.o1[4 * g + 1] = bf_hi(w.x); st.o1[4 * g + 2] = bf_lo(w.y); st.o1[4 * g + 3] = bf_hi(w.y); }
;                             else { st.o0[4 * g] = bf_lo(w.x); st.o0[4 * g + 1] = bf_hi(w.x); st.o0[4 * g + 2] = bf_lo(w.y); st.o0[4 * g + 3] = bf_hi(w.y); } } }
;                 const int vd = h * 64 + r32; const unsigned kc = (unsigned)(C_KD + h * 64 + 8 * hi);
;                 const VSG vs{(const char*)VTD};
;                 {
;                     LA& st = sa; const bf16x8 (&qf)[4] = qa;
;                     auto t16 = [&](int i) -> TP { const int sbr = s0 - 64 + 32 * i; const bool ok = sbr >= 0 && sbr < 1024; const int sb_ = ok ? sbr : s0;
;                         const int t0 = 16 * sb_ + cA, tk = t0 + (lam & 7) * 16 + (lam >> 3) * 128; TP t;
;                         t.koff = ((unsigned)tk * PP + kc) * 2u; t.voff = (unsigned)(vt_off(vd, cA * 1024 + sb_ + 8 * hi) * 2);
;                         t.tp = ok ? (const LAS char*)(tabD16 + (TABD_C + t0 + hi * 128 - tqa)) : negp; t.cb = 0; t.tp2 = t.tp; return t; };
;                     LA_RUN(5, t16, MB_D16, 32, PB, vs);
	global_load_dwordx4 v[80:83], v[6:7], off offset:1024
	global_load_dwordx4 v[84:87], v[2:3], off offset:1536
	global_load_dwordx4 v[88:91], v[4:5], off offset:32
	global_load_dwordx4 v[92:95], v[2:3], off offset:1568
	global_load_dwordx4 v[96:99], v[4:5], off offset:64
	global_load_dwordx4 v[100:103], v[2:3], off offset:1600
	global_load_dwordx4 v[104:107], v[4:5], off offset:96
	global_load_dwordx4 v[108:111], v[2:3], off offset:1632
	v_add_u32_e32 v2, s8, v1
	v_lshl_add_u32 v3, v2, 2, s4
	ds_read_b32 v145, v3
	v_lshrrev_b32_e32 v3, 1, v2
	v_lshrrev_b32_e32 v4, 4, v2
	v_add_u32_e32 v3, v3, v184
	v_add_lshl_u32 v4, v3, v4, 3
	v_lshl_add_u32 v5, v2, 7, 0
	v_and_b32_e32 v6, 0x78, v4
	v_add_u32_e32 v2, v5, v6
	ds_read_b64 v[2:3], v2 offset:36864
	s_or_b32 s6, s8, 4
	v_add_u32_e32 v1, s6, v1
	v_sub_u32_e32 v0, v159, v0
	v_ashrrev_i32_e32 v151, 31, v150
	s_waitcnt lgkmcnt(0)
	v_lshlrev_b32_e32 v32, 16, v2
	v_and_b32_e32 v33, 0xffff0000, v2
	v_add_u32_e32 v2, 16, v4
	v_and_b32_e32 v2, 0x78, v2
	v_add_u32_e32 v2, v5, v2
	v_lshlrev_b32_e32 v34, 16, v3
	v_and_b32_e32 v35, 0xffff0000, v3
	ds_read_b64 v[2:3], v2 offset:36864
	v_lshl_add_u32 v113, v0, 2, 0
	s_waitcnt lgkmcnt(0)
	v_lshlrev_b32_e32 v36, 16, v2
	v_and_b32_e32 v37, 0xffff0000, v2
	v_add_u32_e32 v2, 32, v4
	v_and_b32_e32 v2, 0x78, v2
	v_add_u32_e32 v2, v5, v2
	v_lshlrev_b32_e32 v38, 16, v3
	v_and_b32_e32 v39, 0xffff0000, v3
	ds_read_b64 v[2:3], v2 offset:36864
	s_waitcnt lgkmcnt(0)
	v_lshlrev_b32_e32 v40, 16, v2
	v_and_b32_e32 v41, 0xffff0000, v2
	v_add_u32_e32 v2, 48, v4
	v_and_b32_e32 v2, 0x78, v2
	v_add_u32_e32 v2, v5, v2
	v_lshlrev_b32_e32 v42, 16, v3
	v_and_b32_e32 v43, 0xffff0000, v3
	ds_read_b64 v[2:3], v2 offset:36864
	s_waitcnt lgkmcnt(0)
	v_lshlrev_b32_e32 v44, 16, v2
	v_and_b32_e32 v45, 0xffff0000, v2
	v_xad_u32 v2, v6, 64, v5
	v_lshlrev_b32_e32 v46, 16, v3
	v_and_b32_e32 v47, 0xffff0000, v3
	ds_read_b64 v[2:3], v2 offset:36864
	s_waitcnt lgkmcnt(0)
	v_lshlrev_b32_e32 v16, 16, v2
	v_and_b32_e32 v17, 0xffff0000, v2
	v_add_u32_e32 v2, 0x50, v4
	v_and_b32_e32 v2, 0x78, v2
	v_add_u32_e32 v2, v5, v2
	v_lshlrev_b32_e32 v18, 16, v3
	v_and_b32_e32 v19, 0xffff0000, v3
	ds_read_b64 v[2:3], v2 offset:36864
	s_waitcnt lgkmcnt(0)
	v_lshlrev_b32_e32 v20, 16, v2
	v_and_b32_e32 v21, 0xffff0000, v2
	v_add_u32_e32 v2, 0x60, v4
	v_and_b32_e32 v2, 0x78, v2
	v_add_u32_e32 v2, v5, v2
	v_lshlrev_b32_e32 v22, 16, v3
	v_and_b32_e32 v23, 0xffff0000, v3
	ds_read_b64 v[2:3], v2 offset:36864
	s_waitcnt lgkmcnt(0)
	v_lshlrev_b32_e32 v24, 16, v2
	v_and_b32_e32 v25, 0xffff0000, v2
	v_add_u32_e32 v2, 0x70, v4
	v_and_b32_e32 v2, 0x78, v2
	v_add_u32_e32 v2, v5, v2
	v_lshlrev_b32_e32 v26, 16, v3
	v_and_b32_e32 v27, 0xffff0000, v3
	ds_read_b64 v[2:3], v2 offset:36864
	s_waitcnt lgkmcnt(0)
	v_lshlrev_b32_e32 v28, 16, v2
	v_and_b32_e32 v29, 0xffff0000, v2
	v_lshl_add_u32 v2, v1, 2, s4
	ds_read_b32 v149, v2
	v_lshrrev_b32_e32 v2, 1, v1
	v_lshlrev_b32_e32 v30, 16, v3
	v_and_b32_e32 v31, 0xffff0000, v3
	v_lshrrev_b32_e32 v3, 4, v1
	v_add_u32_e32 v2, v2, v184
	v_add_lshl_u32 v2, v2, v3, 3
	v_lshl_add_u32 v1, v1, 7, 0
	v_and_b32_e32 v3, 0x78, v2
	v_add_u32_e32 v4, v1, v3
	v_xad_u32 v3, v3, 64, v1
	ds_read_b64 v[136:137], v4 offset:36864
	ds_read_b64 v[128:129], v3 offset:36864
	v_add_u32_e32 v4, 16, v2
	v_add_u32_e32 v3, 0x50, v2
	v_and_b32_e32 v4, 0x78, v4
	v_and_b32_e32 v3, 0x78, v3
	v_add_u32_e32 v4, v1, v4
	v_add_u32_e32 v3, v1, v3
	ds_read_b64 v[138:139], v4 offset:36864
	ds_read_b64 v[130:131], v3 offset:36864
	v_add_u32_e32 v4, 32, v2
	v_add_u32_e32 v3, 0x60, v2
	v_and_b32_e32 v4, 0x78, v4
	v_and_b32_e32 v3, 0x78, v3
	s_sub_i32 s4, s1, 64
	v_add_u32_e32 v4, v1, v4
	v_add_u32_e32 v3, v1, v3
	s_cmpk_lt_u32 s4, 0x400
	ds_read_b64 v[140:141], v4 offset:36864
	ds_read_b64 v[132:133], v3 offset:36864
	v_add_u32_e32 v4, 48, v2
	v_add_u32_e32 v2, 0x70, v2
	s_cselect_b32 s4, s4, s1
	v_and_b32_e32 v4, 0x78, v4
	v_and_b32_e32 v2, 0x78, v2
	s_lshl_b32 s5, s4, 4
	v_add_u32_e32 v4, v1, v4
	v_add_u32_e32 v1, v1, v2
	v_add_u32_e32 v2, s5, v112
	v_mul_lo_u32 v2, v2, s67
	v_add_lshl_u32 v2, v2, v181, 1
	ds_read_b64 v[142:143], v4 offset:36864
	ds_read_b64 v[134:135], v1 offset:36864
	global_load_dwordx4 v[60:63], v2, s[74:75]
	global_load_dwordx4 v[56:59], v2, s[74:75] offset:32
	global_load_dwordx4 v[52:55], v2, s[74:75] offset:64
	global_load_dwordx4 v[48:51], v2, s[74:75] offset:96
	s_lshl_b32 s7, s8, 10
	s_add_i32 s9, s4, s7
	v_lshl_add_u32 v1, s9, 1, v154
	v_or_b32_e32 v1, v1, v147
	v_add_u32_e32 v1, v1, v146
	s_movk_i32 s8, 0xffc0
	s_branch .LBB0_696

; __device__ __forceinline__ unsigned cvt_pk_bf16(float lo, float hi) { f32x2_c v = {lo, hi}; bf16x2_c b = __builtin_convertvector(v, bf16x2_c); return __builtin_bit_cast(unsigned, b); }
; __device__ __forceinline__ float silu_f(float z) { return z * __builtin_amdgcn_rcpf(1.f + __expf(-z)); }
; __device__ __forceinline__ void la_loadz(u32x2 (&z)[8], const bf16_t* zrow, int hi) {
; #pragma unroll
;     for (int db = 0; db < 2; ++db)
; #pragma unroll
;         for (int g = 0; g < 4; ++g) z[4 * db + g] = *(const u32x2*)(zrow + 32 * db + 8 * g + 4 * hi);
; }
; __device__ __forceinline__ void la_store(const LA& st, bool use_sink, float sink2, const u32x2 (&zv)[8], bf16_t* yrow, int hi) {
;     float l = st.l; { auto rr = __builtin_amdgcn_permlane32_swap(__float_as_uint(l), __float_as_uint(l), false, false); l = __uint_as_float(rr[0]) + __uint_as_float(rr[1]); }
;     float inv;
;     if (use_sink) { const float m2 = fmaxf(st.m, sink2), a = __builtin_amdgcn_exp2f(st.m - m2); inv = a * __builtin_amdgcn_rcpf(l * a + __builtin_amdgcn_exp2f(sink2 - m2)); }
;     else inv = __builtin_amdgcn_rcpf(l);
; #pragma unroll
;     for (int db = 0; db < 2; ++db)
; #pragma unroll
;         for (int g = 0; g < 4; ++g) { const int c = 32 * db + 8 * g + 4 * hi; const u32x2 z = zv[4 * db + g];
;             const f32x16& o = db ? st.o1 : st.o0;
;             u32x2 w; w.x = cvt_pk_bf16(o[4 * g] * inv * silu_f(bf_lo(z.x)), o[4 * g + 1] * inv * silu_f(bf_hi(z.x)));
;             w.y = cvt_pk_bf16(o[4 * g + 2] * inv * silu_f(bf_lo(z.y)), o[4 * g + 3] * inv * silu_f(bf_hi(z.y)));
;             *(u32x2*)(yrow + c) = w; }
; __global__ void __launch_bounds__(NWAVES * 64, 2) mk_fwd(Args args) {
;     ...
;                 u32x2 zv[8];
;                 la_loadz(zv, PROJ + (size_t)tqa * PP + C_ZD + h * 64, hi); la_store(sa, false, 0.f, zv, Yb + (size_t)tqa * DMODEL + 1536 + h * 64, hi);
.LBB0_708:
	v_mov_b32_e32 v145, v189
	v_lshl_add_u64 v[64:65], v[152:153], 0, v[144:145]
	s_mov_b64 s[4:5], 0x3000
	v_lshl_add_u64 v[68:69], v[64:65], 0, s[4:5]
	v_add_co_u32_e32 v64, vcc, 0x3000, v64
	v_ashrrev_i32_e32 v149, 31, v148
	s_nop 0
	v_addc_co_u32_e32 v65, vcc, 0, v65, vcc
	global_load_dwordx2 v[80:81], v[64:65], off
	global_load_dwordx2 v[78:79], v[68:69], off offset:16
	global_load_dwordx2 v[76:77], v[68:69], off offset:32
	global_load_dwordx2 v[74:75], v[68:69], off offset:48
	global_load_dwordx2 v[72:73], v[68:69], off offset:64
	global_load_dwordx2 v[70:71], v[68:69], off offset:80
	global_load_dwordx2 v[66:67], v[68:69], off offset:96
	global_load_dwordx2 v[64:65], v[68:69], off offset:112
	v_lshlrev_b64 v[68:69], 12, v[150:151]
	v_lshl_add_u64 v[68:69], s[42:43], 0, v[68:69]
	v_lshl_add_u64 v[82:83], v[68:69], 0, s[70:71]
	v_mov_b32_e32 v68, v158
	s_nop 1
	v_permlane32_swap_b32_e32 v158, v68
	v_add_f32_e32 v68, v158, v68
	v_rcp_f32_e32 v68, v68
	v_readlane_b32 s26, v255, 40
	v_readlane_b32 s27, v255, 41
	s_mov_b32 s28, s76
	s_mov_b64 s[40:41], 0x800
	s_mov_b32 s36, s77
	s_waitcnt vmcnt(7)
	v_lshlrev_b32_e32 v84, 16, v80
	v_mul_f32_e32 v69, 0xbfb8aa3b, v84
	v_exp_f32_e32 v69, v69
	v_and_b32_e32 v85, 0xffff0000, v80
	v_add_f32_e32 v69, 1.0, v69
	v_rcp_f32_e32 v86, v69
	v_pk_mul_f32 v[32:33], v[32:33], v[68:69] op_sel_hi:[1,0]
	v_mul_f32_e32 v69, 0xbfb8aa3b, v85
	v_exp_f32_e32 v69, v69
	s_nop 0
	v_add_f32_e32 v69, 1.0, v69
	v_rcp_f32_e32 v87, v69
	s_nop 0
	v_pk_mul_f32 v[84:85], v[86:87], v[84:85]
	s_nop 0
	v_pk_mul_f32 v[32:33], v[84:85], v[32:33]
	s_nop 0
	v_cvt_pk_bf16_f32 v80, v32, v33
	v_lshlrev_b32_e32 v32, 16, v81
	v_mul_f32_e32 v69, 0xbfb8aa3b, v32
	v_exp_f32_e32 v69, v69
	v_and_b32_e32 v33, 0xffff0000, v81
	v_add_f32_e32 v69, 1.0, v69
	v_rcp_f32_e32 v84, v69
	v_pk_mul_f32 v[34:35], v[34:35], v[68:69] op_sel_hi:[1,0]
	v_mul_f32_e32 v69, 0xbfb8aa3b, v33
	v_exp_f32_e32 v69, v69
	s_nop 0
	v_add_f32_e32 v69, 1.0, v69
	v_rcp_f32_e32 v85, v69
	s_nop 0
	v_pk_mul_f32 v[32:33], v[84:85], v[32:33]
	s_nop 0
	v_pk_mul_f32 v[32:33], v[32:33], v[34:35]
	s_waitcnt vmcnt(6)
	v_lshlrev_b32_e32 v34, 16, v78
	v_mul_f32_e32 v69, 0xbfb8aa3b, v34
	v_exp_f32_e32 v69, v69
	v_cvt_pk_bf16_f32 v81, v32, v33
	v_lshl_add_u64 v[32:33], v[82:83], 0, v[144:145]
	v_and_b32_e32 v35, 0xffff0000, v78
	v_add_f32_e32 v69, 1.0, v69
	v_lshrrev_b32_e32 v236, 2, v252
	v_and_b32_e32 v236, 8, v236
	v_add_u32_e32 v234, v32, v236
	v_mov_b32_e32 v235, v33
	v_mov_b32_e32 v228, v80
	v_mov_b32_e32 v229, v81
	v_rcp_f32_e32 v80, v69
	v_pk_mul_f32 v[36:37], v[36:37], v[68:69] op_sel_hi:[1,0]
	v_mul_f32_e32 v69, 0xbfb8aa3b, v35
	v_exp_f32_e32 v69, v69
	s_nop 0
	v_add_f32_e32 v69, 1.0, v69
	v_rcp_f32_e32 v81, v69
	v_pk_mul_f32 v[38:39], v[38:39], v[68:69] op_sel_hi:[1,0]
	v_pk_mul_f32 v[16:17], v[16:17], v[68:69] op_sel_hi:[1,0]
	v_pk_mul_f32 v[18:19], v[18:19], v[68:69] op_sel_hi:[1,0]
	v_pk_mul_f32 v[34:35], v[80:81], v[34:35]
	v_pk_mul_f32 v[20:21], v[20:21], v[68:69] op_sel_hi:[1,0]
	v_pk_mul_f32 v[34:35], v[34:35], v[36:37]
	v_lshlrev_b32_e32 v36, 16, v79
	v_cvt_pk_bf16_f32 v34, v34, v35
	v_mul_f32_e32 v35, 0xbfb8aa3b, v36
	v_exp_f32_e32 v35, v35
	v_and_b32_e32 v37, 0xffff0000, v79
	v_pk_mul_f32 v[22:23], v[22:23], v[68:69] op_sel_hi:[1,0]
	v_add_f32_e32 v35, 1.0, v35
	v_rcp_f32_e32 v78, v35
	v_mul_f32_e32 v35, 0xbfb8aa3b, v37
	v_exp_f32_e32 v35, v35
	s_nop 0
	v_add_f32_e32 v35, 1.0, v35
	v_rcp_f32_e32 v79, v35
	s_nop 0
	v_pk_mul_f32 v[36:37], v[78:79], v[36:37]
	s_nop 0
	v_pk_mul_f32 v[36:37], v[36:37], v[38:39]
	v_pk_mul_f32 v[38:39], v[40:41], v[68:69] op_sel_hi:[1,0]
	v_cvt_pk_bf16_f32 v35, v36, v37
	v_mov_b32_e32 v230, v34
	v_mov_b32_e32 v231, v35
	s_nop 1
	v_permlane32_swap_b32_e32 v228, v230
	v_permlane32_swap_b32_e32 v229, v231
	global_store_dwordx4 v[234:235], v[228:231], off offset:3072
	s_waitcnt vmcnt(6)
	v_lshlrev_b32_e32 v34, 16, v76
	v_and_b32_e32 v35, 0xffff0000, v76
	v_mul_f32_e32 v36, 0xbfb8aa3b, v34
	v_mul_f32_e32 v37, 0xbfb8aa3b, v35
	v_exp_f32_e32 v36, v36
	v_exp_f32_e32 v37, v37
	v_pk_mul_f32 v[40:41], v[42:43], v[68:69] op_sel_hi:[1,0]
	v_add_f32_e32 v36, 1.0, v36
	v_add_f32_e32 v37, 1.0, v37
	v_rcp_f32_e32 v36, v36
	v_rcp_f32_e32 v37, v37
	s_nop 0
	v_pk_mul_f32 v[34:35], v[36:37], v[34:35]
	s_nop 0
	v_pk_mul_f32 v[34:35], v[34:35], v[38:39]
	v_lshlrev_b32_e32 v36, 16, v77
	v_cvt_pk_bf16_f32 v34, v34, v35
	v_mul_f32_e32 v35, 0xbfb8aa3b, v36
	v_exp_f32_e32 v35, v35
	v_and_b32_e32 v37, 0xffff0000, v77
	v_add_f32_e32 v35, 1.0, v35
	v_rcp_f32_e32 v38, v35
	v_mul_f32_e32 v35, 0xbfb8aa3b, v37
	v_exp_f32_e32 v35, v35
	s_nop 0
	v_add_f32_e32 v35, 1.0, v35
	v_rcp_f32_e32 v39, v35
	s_nop 0
	v_pk_mul_f32 v[36:37], v[38:39], v[36:37]
	s_nop 0
	v_pk_mul_f32 v[36:37], v[36:37], v[40:41]
	v_pk_mul_f32 v[38:39], v[44:45], v[68:69] op_sel_hi:[1,0]
	v_cvt_pk_bf16_f32 v35, v36, v37
	v_mov_b32_e32 v228, v34
	v_mov_b32_e32 v229, v35
	s_waitcnt vmcnt(5)
	v_lshlrev_b32_e32 v34, 16, v74
	v_and_b32_e32 v35, 0xffff0000, v74
	v_mul_f32_e32 v36, 0xbfb8aa3b, v34
	v_mul_f32_e32 v37, 0xbfb8aa3b, v35
	v_exp_f32_e32 v36, v36
	v_exp_f32_e32 v37, v37
	v_pk_mul_f32 v[40:41], v[46:47], v[68:69] op_sel_hi:[1,0]
	v_add_f32_e32 v36, 1.0, v36
	v_add_f32_e32 v37, 1.0, v37
	v_rcp_f32_e32 v36, v36
	v_rcp_f32_e32 v37, v37
	s_nop 0
	v_pk_mul_f32 v[34:35], v[36:37], v[34:35]
	s_nop 0
	v_pk_mul_f32 v[34:35], v[34:35], v[38:39]
	v_lshlrev_b32_e32 v36, 16, v75
	v_cvt_pk_bf16_f32 v34, v34, v35
	v_mul_f32_e32 v35, 0xbfb8aa3b, v36
	v_exp_f32_e32 v35, v35
	v_and_b32_e32 v37, 0xffff0000, v75
	v_add_f32_e32 v35, 1.0, v35
	v_rcp_f32_e32 v38, v35
	v_mul_f32_e32 v35, 0xbfb8aa3b, v37
	v_exp_f32_e32 v35, v35
	s_nop 0
	v_add_f32_e32 v35, 1.0, v35
	v_rcp_f32_e32 v39, v35
	s_nop 0
	v_pk_mul_f32 v[36:37], v[38:39], v[36:37]
	s_nop 0
	v_pk_mul_f32 v[36:37], v[36:37], v[40:41]
	s_nop 0
	v_cvt_pk_bf16_f32 v35, v36, v37
	v_mov_b32_e32 v230, v34
	v_mov_b32_e32 v231, v35
	s_nop 1
	v_permlane32_swap_b32_e32 v228, v230
	v_permlane32_swap_b32_e32 v229, v231
	global_store_dwordx4 v[234:235], v[228:231], off offset:3104
	s_waitcnt vmcnt(5)
; __device__ __forceinline__ unsigned cvt_pk_bf16(float lo, float hi) { f32x2_c v = {lo, hi}; bf16x2_c b = __builtin_convertvector(v, bf16x2_c); return __builtin_bit_cast(unsigned, b); }
; __device__ __forceinline__ float silu_f(float z) { return z * __builtin_amdgcn_rcpf(1.f + __expf(-z)); }
; __device__ __forceinline__ void la_loadz(u32x2 (&z)[8], const bf16_t* zrow, int hi) {
; #pragma unroll
;     for (int db = 0; db < 2; ++db)
; #pragma unroll
;         for (int g = 0; g < 4; ++g) z[4 * db + g] = *(const u32x2*)(zrow + 32 * db + 8 * g + 4 * hi);
; }
; __device__ __forceinline__ void la_store(const LA& st, bool use_sink, float sink2, const u32x2 (&zv)[8], bf16_t* yrow, int hi) {
;     float l = st.l; { auto rr = __builtin_amdgcn_permlane32_swap(__float_as_uint(l), __float_as_uint(l), false, false); l = __uint_as_float(rr[0]) + __uint_as_float(rr[1]); }
;     float inv;
;     if (use_sink) { const float m2 = fmaxf(st.m, sink2), a = __builtin_amdgcn_exp2f(st.m - m2); inv = a * __builtin_amdgcn_rcpf(l * a + __builtin_amdgcn_exp2f(sink2 - m2)); }
;     else inv = __builtin_amdgcn_rcpf(l);
; #pragma unroll
;     for (int db = 0; db < 2; ++db)
; #pragma unroll
;         for (int g = 0; g < 4; ++g) { const int c = 32 * db + 8 * g + 4 * hi; const u32x2 z = zv[4 * db + g];
;             const f32x16& o = db ? st.o1 : st.o0;
;             u32x2 w; w.x = cvt_pk_bf16(o[4 * g] * inv * silu_f(bf_lo(z.x)), o[4 * g + 1] * inv * silu_f(bf_hi(z.x)));
;             w.y = cvt_pk_bf16(o[4 * g + 2] * inv * silu_f(bf_lo(z.y)), o[4 * g + 3] * inv * silu_f(bf_hi(z.y)));
;             *(u32x2*)(yrow + c) = w; }
; __global__ void __launch_bounds__(NWAVES * 64, 2) mk_fwd(Args args) {
;     ...
;                 la_loadz(zv, PROJ + (size_t)tqa * PP + C_ZD + h * 64, hi); la_store(sa, false, 0.f, zv, Yb + (size_t)tqa * DMODEL + 1536 + h * 64, hi);
;                 la_loadz(zv, PROJ + (size_t)tqb * PP + C_ZD + h * 64, hi); la_store(sb, false, 0.f, zv, Yb + (size_t)tqb * DMODEL + 1536 + h * 64, hi);
	v_lshlrev_b32_e32 v34, 16, v72
	v_and_b32_e32 v35, 0xffff0000, v72
	v_mul_f32_e32 v36, 0xbfb8aa3b, v34
	v_mul_f32_e32 v37, 0xbfb8aa3b, v35
	v_exp_f32_e32 v36, v36
	v_exp_f32_e32 v37, v37
	v_add_f32_e32 v36, 1.0, v36
	v_add_f32_e32 v37, 1.0, v37
	v_rcp_f32_e32 v36, v36
	v_rcp_f32_e32 v37, v37
	s_nop 0
	v_pk_mul_f32 v[34:35], v[36:37], v[34:35]
	s_nop 0
	v_pk_mul_f32 v[16:17], v[34:35], v[16:17]
	v_lshlrev_b32_e32 v34, 16, v73
	v_cvt_pk_bf16_f32 v16, v16, v17
	v_mul_f32_e32 v17, 0xbfb8aa3b, v34
	v_exp_f32_e32 v17, v17
	v_and_b32_e32 v35, 0xffff0000, v73
	v_add_f32_e32 v17, 1.0, v17
	v_rcp_f32_e32 v36, v17
	v_mul_f32_e32 v17, 0xbfb8aa3b, v35
	v_exp_f32_e32 v17, v17
	s_nop 0
	v_add_f32_e32 v17, 1.0, v17
	v_rcp_f32_e32 v37, v17
	s_nop 0
	v_pk_mul_f32 v[34:35], v[36:37], v[34:35]
	s_nop 0
	v_pk_mul_f32 v[18:19], v[34:35], v[18:19]
	s_nop 0
	v_cvt_pk_bf16_f32 v17, v18, v19
	v_mov_b32_e32 v228, v16
	v_mov_b32_e32 v229, v17
	s_waitcnt vmcnt(4)
	v_lshlrev_b32_e32 v16, 16, v70
	v_and_b32_e32 v17, 0xffff0000, v70
	v_mul_f32_e32 v18, 0xbfb8aa3b, v16
	v_mul_f32_e32 v19, 0xbfb8aa3b, v17
	v_exp_f32_e32 v18, v18
	v_exp_f32_e32 v19, v19
	v_add_f32_e32 v18, 1.0, v18
	v_add_f32_e32 v19, 1.0, v19
	v_rcp_f32_e32 v18, v18
	v_rcp_f32_e32 v19, v19
	s_nop 0
	v_pk_mul_f32 v[16:17], v[18:19], v[16:17]
	s_nop 0
	v_pk_mul_f32 v[16:17], v[20:21], v[16:17]
	v_lshlrev_b32_e32 v18, 16, v71
	v_cvt_pk_bf16_f32 v16, v16, v17
	v_mul_f32_e32 v17, 0xbfb8aa3b, v18
	v_exp_f32_e32 v17, v17
	v_and_b32_e32 v19, 0xffff0000, v71
	v_add_f32_e32 v17, 1.0, v17
	v_rcp_f32_e32 v20, v17
	v_mul_f32_e32 v17, 0xbfb8aa3b, v19
	v_exp_f32_e32 v17, v17
	s_nop 0
	v_add_f32_e32 v17, 1.0, v17
	v_rcp_f32_e32 v21, v17
	s_nop 0
	v_pk_mul_f32 v[18:19], v[20:21], v[18:19]
	s_nop 0
	v_pk_mul_f32 v[18:19], v[22:23], v[18:19]
	v_pk_mul_f32 v[20:21], v[24:25], v[68:69] op_sel_hi:[1,0]
	v_cvt_pk_bf16_f32 v17, v18, v19
	v_mov_b32_e32 v230, v16
	v_mov_b32_e32 v231, v17
	s_nop 1
	v_permlane32_swap_b32_e32 v228, v230
	v_permlane32_swap_b32_e32 v229, v231
	global_store_dwordx4 v[234:235], v[228:231], off offset:3136
	s_waitcnt vmcnt(4)
	v_lshlrev_b32_e32 v16, 16, v66
	v_and_b32_e32 v17, 0xffff0000, v66
	v_mul_f32_e32 v18, 0xbfb8aa3b, v16
	v_mul_f32_e32 v19, 0xbfb8aa3b, v17
	v_exp_f32_e32 v18, v18
	v_exp_f32_e32 v19, v19
	v_pk_mul_f32 v[22:23], v[26:27], v[68:69] op_sel_hi:[1,0]
	v_add_f32_e32 v18, 1.0, v18
	v_add_f32_e32 v19, 1.0, v19
	v_rcp_f32_e32 v18, v18
	v_rcp_f32_e32 v19, v19
	s_nop 0
	v_pk_mul_f32 v[16:17], v[18:19], v[16:17]
	s_nop 0
	v_pk_mul_f32 v[16:17], v[20:21], v[16:17]
	v_lshlrev_b32_e32 v18, 16, v67
	v_cvt_pk_bf16_f32 v16, v16, v17
	v_mul_f32_e32 v17, 0xbfb8aa3b, v18
	v_exp_f32_e32 v17, v17
	v_and_b32_e32 v19, 0xffff0000, v67
	v_add_f32_e32 v17, 1.0, v17
	v_rcp_f32_e32 v20, v17
	v_mul_f32_e32 v17, 0xbfb8aa3b, v19
	v_exp_f32_e32 v17, v17
	s_nop 0
	v_add_f32_e32 v17, 1.0, v17
	v_rcp_f32_e32 v21, v17
	s_nop 0
	v_pk_mul_f32 v[18:19], v[20:21], v[18:19]
	s_nop 0
	v_pk_mul_f32 v[18:19], v[22:23], v[18:19]
	v_pk_mul_f32 v[20:21], v[28:29], v[68:69] op_sel_hi:[1,0]
	v_cvt_pk_bf16_f32 v17, v18, v19
	v_mov_b32_e32 v228, v16
	v_mov_b32_e32 v229, v17
	s_waitcnt vmcnt(3)
	v_lshlrev_b32_e32 v16, 16, v64
	v_and_b32_e32 v17, 0xffff0000, v64
	v_mul_f32_e32 v18, 0xbfb8aa3b, v16
	v_mul_f32_e32 v19, 0xbfb8aa3b, v17
	v_exp_f32_e32 v18, v18
	v_exp_f32_e32 v19, v19
	v_pk_mul_f32 v[22:23], v[30:31], v[68:69] op_sel_hi:[1,0]
	v_add_f32_e32 v18, 1.0, v18
	v_add_f32_e32 v19, 1.0, v19
	v_rcp_f32_e32 v18, v18
	v_rcp_f32_e32 v19, v19
	s_nop 0
	v_pk_mul_f32 v[16:17], v[18:19], v[16:17]
	s_nop 0
	v_pk_mul_f32 v[16:17], v[20:21], v[16:17]
	v_lshlrev_b32_e32 v18, 16, v65
	v_cvt_pk_bf16_f32 v16, v16, v17
	v_mul_f32_e32 v17, 0xbfb8aa3b, v18
	v_exp_f32_e32 v17, v17
	v_and_b32_e32 v19, 0xffff0000, v65
	v_add_f32_e32 v17, 1.0, v17
	v_rcp_f32_e32 v20, v17
	v_mul_f32_e32 v17, 0xbfb8aa3b, v19
	v_exp_f32_e32 v17, v17
	s_nop 0
	v_add_f32_e32 v17, 1.0, v17
	v_rcp_f32_e32 v21, v17
	s_nop 0
	v_pk_mul_f32 v[18:19], v[20:21], v[18:19]
	s_nop 0
	v_pk_mul_f32 v[18:19], v[22:23], v[18:19]
	s_nop 0
	v_cvt_pk_bf16_f32 v17, v18, v19
	v_mov_b32_e32 v230, v16
	v_mov_b32_e32 v231, v17
	s_nop 1
	v_permlane32_swap_b32_e32 v228, v230
	v_permlane32_swap_b32_e32 v229, v231
	global_store_dwordx4 v[234:235], v[228:231], off offset:3168
	v_mov_b64_e32 v[16:17], s[74:75]
	v_mad_i64_i32 v[16:17], s[0:1], v148, s64, v[16:17]
	v_lshl_add_u64 v[16:17], v[16:17], 0, s[70:71]
	v_lshl_add_u64 v[18:19], v[16:17], 0, v[144:145]
	s_movk_i32 s0, 0x3000
	v_lshl_add_u64 v[16:17], v[18:19], 0, s[4:5]
	v_add_co_u32_e32 v18, vcc, s0, v18
	s_nop 1
	v_addc_co_u32_e32 v19, vcc, 0, v19, vcc
	global_load_dwordx2 v[20:21], v[18:19], off
	global_load_dwordx2 v[32:33], v[16:17], off offset:16
	global_load_dwordx2 v[30:31], v[16:17], off offset:32
	global_load_dwordx2 v[28:29], v[16:17], off offset:48
	global_load_dwordx2 v[26:27], v[16:17], off offset:64
	global_load_dwordx2 v[24:25], v[16:17], off offset:80
	global_load_dwordx2 v[22:23], v[16:17], off offset:96
	s_nop 0
	global_load_dwordx2 v[16:17], v[16:17], off offset:112
	v_lshlrev_b64 v[18:19], 12, v[148:149]
	v_lshl_add_u64 v[18:19], s[42:43], 0, v[18:19]
	v_lshl_add_u64 v[34:35], v[18:19], 0, s[70:71]
	v_mov_b32_e32 v18, v156
	s_nop 1
	v_permlane32_swap_b32_e32 v156, v18
	v_add_f32_e32 v18, v156, v18
	v_rcp_f32_e32 v18, v18
	s_waitcnt vmcnt(7)
; __device__ __forceinline__ unsigned cvt_pk_bf16(float lo, float hi) { f32x2_c v = {lo, hi}; bf16x2_c b = __builtin_convertvector(v, bf16x2_c); return __builtin_bit_cast(unsigned, b); }
; __device__ __forceinline__ float silu_f(float z) { return z * __builtin_amdgcn_rcpf(1.f + __expf(-z)); }
; __device__ __forceinline__ void la_store(const LA& st, bool use_sink, float sink2, const u32x2 (&zv)[8], bf16_t* yrow, int hi) {
;     float l = st.l; { auto rr = __builtin_amdgcn_permlane32_swap(__float_as_uint(l), __float_as_uint(l), false, false); l = __uint_as_float(rr[0]) + __uint_as_float(rr[1]); }
;     float inv;
;     if (use_sink) { const float m2 = fmaxf(st.m, sink2), a = __builtin_amdgcn_exp2f(st.m - m2); inv = a * __builtin_amdgcn_rcpf(l * a + __builtin_amdgcn_exp2f(sink2 - m2)); }
;     else inv = __builtin_amdgcn_rcpf(l);
; #pragma unroll
;     for (int db = 0; db < 2; ++db)
; #pragma unroll
;         for (int g = 0; g < 4; ++g) { const int c = 32 * db + 8 * g + 4 * hi; const u32x2 z = zv[4 * db + g];
;             const f32x16& o = db ? st.o1 : st.o0;
;             u32x2 w; w.x = cvt_pk_bf16(o[4 * g] * inv * silu_f(bf_lo(z.x)), o[4 * g + 1] * inv * silu_f(bf_hi(z.x)));
;             w.y = cvt_pk_bf16(o[4 * g + 2] * inv * silu_f(bf_lo(z.y)), o[4 * g + 3] * inv * silu_f(bf_hi(z.y)));
;             *(u32x2*)(yrow + c) = w; }
; __global__ void __launch_bounds__(NWAVES * 64, 2) mk_fwd(Args args) {
;     ...
;                 la_loadz(zv, PROJ + (size_t)tqb * PP + C_ZD + h * 64, hi); la_store(sb, false, 0.f, zv, Yb + (size_t)tqb * DMODEL + 1536 + h * 64, hi);
	v_lshlrev_b32_e32 v36, 16, v20
	v_mul_f32_e32 v19, 0xbfb8aa3b, v36
	v_exp_f32_e32 v19, v19
	v_and_b32_e32 v37, 0xffff0000, v20
	v_lshlrev_b32_e32 v20, 16, v21
	v_and_b32_e32 v21, 0xffff0000, v21
	v_add_f32_e32 v19, 1.0, v19
	v_rcp_f32_e32 v38, v19
	v_pk_mul_f32 v[40:41], v[48:49], v[18:19] op_sel_hi:[1,0]
	v_mul_f32_e32 v19, 0xbfb8aa3b, v37
	v_exp_f32_e32 v19, v19
	s_nop 0
	v_add_f32_e32 v19, 1.0, v19
	v_rcp_f32_e32 v39, v19
	v_mul_f32_e32 v19, 0xbfb8aa3b, v20
	v_exp_f32_e32 v19, v19
	v_pk_mul_f32 v[36:37], v[38:39], v[36:37]
	s_nop 0
	v_pk_mul_f32 v[36:37], v[36:37], v[40:41]
	v_add_f32_e32 v19, 1.0, v19
	v_rcp_f32_e32 v38, v19
	v_pk_mul_f32 v[40:41], v[50:51], v[18:19] op_sel_hi:[1,0]
	v_mul_f32_e32 v19, 0xbfb8aa3b, v21
	v_exp_f32_e32 v19, v19
	v_cvt_pk_bf16_f32 v36, v36, v37
	v_add_f32_e32 v19, 1.0, v19
	v_rcp_f32_e32 v39, v19
	s_nop 0
	v_pk_mul_f32 v[20:21], v[38:39], v[20:21]
	s_nop 0
	v_pk_mul_f32 v[20:21], v[20:21], v[40:41]
	s_nop 0
	v_cvt_pk_bf16_f32 v37, v20, v21
	v_lshl_add_u64 v[20:21], v[34:35], 0, v[144:145]
	s_waitcnt vmcnt(6)
	v_lshlrev_b32_e32 v34, 16, v32
	v_mul_f32_e32 v19, 0xbfb8aa3b, v34
	v_exp_f32_e32 v19, v19
	v_and_b32_e32 v35, 0xffff0000, v32
	v_lshrrev_b32_e32 v236, 2, v252
	v_and_b32_e32 v236, 8, v236
	v_add_u32_e32 v234, v20, v236
	v_mov_b32_e32 v235, v21
	v_mov_b32_e32 v228, v36
	v_mov_b32_e32 v229, v37
	v_add_f32_e32 v19, 1.0, v19
	v_rcp_f32_e32 v36, v19
	v_pk_mul_f32 v[38:39], v[52:53], v[18:19] op_sel_hi:[1,0]
	v_mul_f32_e32 v19, 0xbfb8aa3b, v35
	v_exp_f32_e32 v19, v19
	s_nop 0
	v_add_f32_e32 v19, 1.0, v19
	v_rcp_f32_e32 v37, v19
	s_nop 0
	v_pk_mul_f32 v[34:35], v[36:37], v[34:35]
	s_nop 0
	v_pk_mul_f32 v[34:35], v[34:35], v[38:39]
	s_nop 0
	v_cvt_pk_bf16_f32 v32, v34, v35
	v_lshlrev_b32_e32 v34, 16, v33
	v_mul_f32_e32 v19, 0xbfb8aa3b, v34
	v_exp_f32_e32 v19, v19
	v_and_b32_e32 v35, 0xffff0000, v33
	v_add_f32_e32 v19, 1.0, v19
	v_rcp_f32_e32 v36, v19
	v_pk_mul_f32 v[38:39], v[54:55], v[18:19] op_sel_hi:[1,0]
	v_mul_f32_e32 v19, 0xbfb8aa3b, v35
	v_exp_f32_e32 v19, v19
	s_nop 0
	v_add_f32_e32 v19, 1.0, v19
	v_rcp_f32_e32 v37, v19
	s_nop 0
	v_pk_mul_f32 v[34:35], v[36:37], v[34:35]
	s_nop 0
	v_pk_mul_f32 v[34:35], v[34:35], v[38:39]
	s_nop 0
	v_cvt_pk_bf16_f32 v33, v34, v35
	v_mov_b32_e32 v230, v32
	v_mov_b32_e32 v231, v33
	s_nop 1
	v_permlane32_swap_b32_e32 v228, v230
	v_permlane32_swap_b32_e32 v229, v231
	global_store_dwordx4 v[234:235], v[228:231], off offset:3072
	s_waitcnt vmcnt(6)
	v_lshlrev_b32_e32 v32, 16, v30
	v_mul_f32_e32 v19, 0xbfb8aa3b, v32
	v_exp_f32_e32 v19, v19
	v_and_b32_e32 v33, 0xffff0000, v30
	v_add_f32_e32 v19, 1.0, v19
	v_rcp_f32_e32 v34, v19
	v_pk_mul_f32 v[36:37], v[56:57], v[18:19] op_sel_hi:[1,0]
	v_mul_f32_e32 v19, 0xbfb8aa3b, v33
	v_exp_f32_e32 v19, v19
	s_nop 0
	v_add_f32_e32 v19, 1.0, v19
	v_rcp_f32_e32 v35, v19
	s_nop 0
	v_pk_mul_f32 v[32:33], v[34:35], v[32:33]
	s_nop 0
	v_pk_mul_f32 v[32:33], v[32:33], v[36:37]
	s_nop 0
	v_cvt_pk_bf16_f32 v30, v32, v33
	v_lshlrev_b32_e32 v32, 16, v31
	v_mul_f32_e32 v19, 0xbfb8aa3b, v32
	v_exp_f32_e32 v19, v19
	v_and_b32_e32 v33, 0xffff0000, v31
	v_add_f32_e32 v19, 1.0, v19
	v_rcp_f32_e32 v34, v19
	v_pk_mul_f32 v[36:37], v[58:59], v[18:19] op_sel_hi:[1,0]
	v_mul_f32_e32 v19, 0xbfb8aa3b, v33
	v_exp_f32_e32 v19, v19
	s_nop 0
	v_add_f32_e32 v19, 1.0, v19
	v_rcp_f32_e32 v35, v19
	s_nop 0
	v_pk_mul_f32 v[32:33], v[34:35], v[32:33]
	s_nop 0
	v_pk_mul_f32 v[32:33], v[32:33], v[36:37]
	s_nop 0
	v_cvt_pk_bf16_f32 v31, v32, v33
	v_mov_b32_e32 v228, v30
	v_mov_b32_e32 v229, v31
	s_waitcnt vmcnt(5)
	v_lshlrev_b32_e32 v30, 16, v28
	v_mul_f32_e32 v19, 0xbfb8aa3b, v30
	v_exp_f32_e32 v19, v19
	v_and_b32_e32 v31, 0xffff0000, v28
	v_add_f32_e32 v19, 1.0, v19
	v_rcp_f32_e32 v32, v19
	v_pk_mul_f32 v[34:35], v[60:61], v[18:19] op_sel_hi:[1,0]
	v_mul_f32_e32 v19, 0xbfb8aa3b, v31
	v_exp_f32_e32 v19, v19
	s_nop 0
	v_add_f32_e32 v19, 1.0, v19
	v_rcp_f32_e32 v33, v19
	s_nop 0
	v_pk_mul_f32 v[30:31], v[32:33], v[30:31]
	s_nop 0
	v_pk_mul_f32 v[30:31], v[30:31], v[34:35]
	s_nop 0
	v_cvt_pk_bf16_f32 v28, v30, v31
	v_lshlrev_b32_e32 v30, 16, v29
	v_mul_f32_e32 v19, 0xbfb8aa3b, v30
	v_exp_f32_e32 v19, v19
	v_and_b32_e32 v31, 0xffff0000, v29
	v_add_f32_e32 v19, 1.0, v19
	v_rcp_f32_e32 v32, v19
	v_pk_mul_f32 v[34:35], v[62:63], v[18:19] op_sel_hi:[1,0]
	v_mul_f32_e32 v19, 0xbfb8aa3b, v31
	v_exp_f32_e32 v19, v19
	s_nop 0
	v_add_f32_e32 v19, 1.0, v19
	v_rcp_f32_e32 v33, v19
	s_nop 0
	v_pk_mul_f32 v[30:31], v[32:33], v[30:31]
	s_nop 0
	v_pk_mul_f32 v[30:31], v[30:31], v[34:35]
	s_nop 0
	v_cvt_pk_bf16_f32 v29, v30, v31
	v_mov_b32_e32 v230, v28
	v_mov_b32_e32 v231, v29
	s_nop 1
	v_permlane32_swap_b32_e32 v228, v230
	v_permlane32_swap_b32_e32 v229, v231
	global_store_dwordx4 v[234:235], v[228:231], off offset:3104
	s_waitcnt vmcnt(5)
; __device__ __forceinline__ unsigned cvt_pk_bf16(float lo, float hi) { f32x2_c v = {lo, hi}; bf16x2_c b = __builtin_convertvector(v, bf16x2_c); return __builtin_bit_cast(unsigned, b); }
; __device__ __forceinline__ float silu_f(float z) { return z * __builtin_amdgcn_rcpf(1.f + __expf(-z)); }
; __device__ __forceinline__ void la_store(const LA& st, bool use_sink, float sink2, const u32x2 (&zv)[8], bf16_t* yrow, int hi) {
;     float l = st.l; { auto rr = __builtin_amdgcn_permlane32_swap(__float_as_uint(l), __float_as_uint(l), false, false); l = __uint_as_float(rr[0]) + __uint_as_float(rr[1]); }
;     float inv;
;     if (use_sink) { const float m2 = fmaxf(st.m, sink2), a = __builtin_amdgcn_exp2f(st.m - m2); inv = a * __builtin_amdgcn_rcpf(l * a + __builtin_amdgcn_exp2f(sink2 - m2)); }
;     else inv = __builtin_amdgcn_rcpf(l);
; #pragma unroll
;     for (int db = 0; db < 2; ++db)
; #pragma unroll
;         for (int g = 0; g < 4; ++g) { const int c = 32 * db + 8 * g + 4 * hi; const u32x2 z = zv[4 * db + g];
;             const f32x16& o = db ? st.o1 : st.o0;
;             u32x2 w; w.x = cvt_pk_bf16(o[4 * g] * inv * silu_f(bf_lo(z.x)), o[4 * g + 1] * inv * silu_f(bf_hi(z.x)));
;             w.y = cvt_pk_bf16(o[4 * g + 2] * inv * silu_f(bf_lo(z.y)), o[4 * g + 3] * inv * silu_f(bf_hi(z.y)));
;             *(u32x2*)(yrow + c) = w; }
	v_lshlrev_b32_e32 v28, 16, v26
	v_mul_f32_e32 v19, 0xbfb8aa3b, v28
	v_exp_f32_e32 v19, v19
	v_and_b32_e32 v29, 0xffff0000, v26
	v_lshlrev_b32_e32 v26, 16, v27
	v_and_b32_e32 v27, 0xffff0000, v27
	v_add_f32_e32 v19, 1.0, v19
	v_rcp_f32_e32 v30, v19
	v_pk_mul_f32 v[0:1], v[0:1], v[18:19] op_sel_hi:[1,0]
	v_mul_f32_e32 v19, 0xbfb8aa3b, v29
	v_exp_f32_e32 v19, v19
	s_nop 0
	v_add_f32_e32 v19, 1.0, v19
	v_rcp_f32_e32 v31, v19
	v_pk_mul_f32 v[2:3], v[2:3], v[18:19] op_sel_hi:[1,0]
	v_pk_mul_f32 v[4:5], v[4:5], v[18:19] op_sel_hi:[1,0]
	v_pk_mul_f32 v[6:7], v[6:7], v[18:19] op_sel_hi:[1,0]
	v_pk_mul_f32 v[28:29], v[30:31], v[28:29]
	s_nop 0
	v_pk_mul_f32 v[0:1], v[28:29], v[0:1]
	s_nop 0
	v_cvt_pk_bf16_f32 v0, v0, v1
	v_mul_f32_e32 v1, 0xbfb8aa3b, v26
	v_exp_f32_e32 v1, v1
	s_nop 0
	v_add_f32_e32 v1, 1.0, v1
	v_rcp_f32_e32 v28, v1
	v_mul_f32_e32 v1, 0xbfb8aa3b, v27
	v_exp_f32_e32 v1, v1
	s_nop 0
	v_add_f32_e32 v1, 1.0, v1
	v_rcp_f32_e32 v29, v1
	s_nop 0
	v_pk_mul_f32 v[26:27], v[28:29], v[26:27]
	s_nop 0
	v_pk_mul_f32 v[2:3], v[26:27], v[2:3]
	s_nop 0
	v_cvt_pk_bf16_f32 v1, v2, v3
	v_mov_b32_e32 v228, v0
	v_mov_b32_e32 v229, v1
	s_waitcnt vmcnt(4)
	v_lshlrev_b32_e32 v0, 16, v24
	v_and_b32_e32 v1, 0xffff0000, v24
	v_mul_f32_e32 v2, 0xbfb8aa3b, v0
	v_mul_f32_e32 v3, 0xbfb8aa3b, v1
	v_exp_f32_e32 v2, v2
	v_exp_f32_e32 v3, v3
	v_add_f32_e32 v2, 1.0, v2
	v_add_f32_e32 v3, 1.0, v3
	v_rcp_f32_e32 v2, v2
	v_rcp_f32_e32 v3, v3
	s_nop 0
	v_pk_mul_f32 v[0:1], v[2:3], v[0:1]
	s_nop 0
	v_pk_mul_f32 v[0:1], v[4:5], v[0:1]
	v_lshlrev_b32_e32 v2, 16, v25
	v_cvt_pk_bf16_f32 v0, v0, v1
	v_mul_f32_e32 v1, 0xbfb8aa3b, v2
	v_exp_f32_e32 v1, v1
	v_and_b32_e32 v3, 0xffff0000, v25
	v_add_f32_e32 v1, 1.0, v1
	v_rcp_f32_e32 v4, v1
	v_mul_f32_e32 v1, 0xbfb8aa3b, v3
	v_exp_f32_e32 v1, v1
	s_nop 0
	v_add_f32_e32 v1, 1.0, v1
	v_rcp_f32_e32 v5, v1
	s_nop 0
	v_pk_mul_f32 v[2:3], v[4:5], v[2:3]
	s_nop 0
	v_pk_mul_f32 v[2:3], v[6:7], v[2:3]
	v_pk_mul_f32 v[4:5], v[8:9], v[18:19] op_sel_hi:[1,0]
	v_cvt_pk_bf16_f32 v1, v2, v3
	v_mov_b32_e32 v230, v0
	v_mov_b32_e32 v231, v1
	s_nop 1
	v_permlane32_swap_b32_e32 v228, v230
	v_permlane32_swap_b32_e32 v229, v231
	global_store_dwordx4 v[234:235], v[228:231], off offset:3136
	s_waitcnt vmcnt(4)
	v_lshlrev_b32_e32 v0, 16, v22
	v_and_b32_e32 v1, 0xffff0000, v22
	v_mul_f32_e32 v2, 0xbfb8aa3b, v0
	v_mul_f32_e32 v3, 0xbfb8aa3b, v1
	v_exp_f32_e32 v2, v2
	v_exp_f32_e32 v3, v3
	v_pk_mul_f32 v[6:7], v[10:11], v[18:19] op_sel_hi:[1,0]
	v_add_f32_e32 v2, 1.0, v2
	v_add_f32_e32 v3, 1.0, v3
	v_rcp_f32_e32 v2, v2
	v_rcp_f32_e32 v3, v3
	s_nop 0
	v_pk_mul_f32 v[0:1], v[2:3], v[0:1]
	s_nop 0
	v_pk_mul_f32 v[0:1], v[4:5], v[0:1]
	v_lshlrev_b32_e32 v2, 16, v23
	v_cvt_pk_bf16_f32 v0, v0, v1
	v_mul_f32_e32 v1, 0xbfb8aa3b, v2
	v_exp_f32_e32 v1, v1
	v_and_b32_e32 v3, 0xffff0000, v23
	v_add_f32_e32 v1, 1.0, v1
	v_rcp_f32_e32 v4, v1
	v_mul_f32_e32 v1, 0xbfb8aa3b, v3
	v_exp_f32_e32 v1, v1
	s_nop 0
	v_add_f32_e32 v1, 1.0, v1
	v_rcp_f32_e32 v5, v1
	s_nop 0
	v_pk_mul_f32 v[2:3], v[4:5], v[2:3]
	s_nop 0
	v_pk_mul_f32 v[2:3], v[6:7], v[2:3]
	v_pk_mul_f32 v[4:5], v[12:13], v[18:19] op_sel_hi:[1,0]
	v_cvt_pk_bf16_f32 v1, v2, v3
	v_mov_b32_e32 v228, v0
	v_mov_b32_e32 v229, v1
	s_waitcnt vmcnt(3)
	v_lshlrev_b32_e32 v0, 16, v16
	v_and_b32_e32 v1, 0xffff0000, v16
	v_mul_f32_e32 v2, 0xbfb8aa3b, v0
	v_mul_f32_e32 v3, 0xbfb8aa3b, v1
	v_exp_f32_e32 v2, v2
	v_exp_f32_e32 v3, v3
	v_pk_mul_f32 v[6:7], v[14:15], v[18:19] op_sel_hi:[1,0]
	v_add_f32_e32 v2, 1.0, v2
	v_add_f32_e32 v3, 1.0, v3
	v_rcp_f32_e32 v2, v2
	v_rcp_f32_e32 v3, v3
	s_nop 0
	v_pk_mul_f32 v[0:1], v[2:3], v[0:1]
	s_nop 0
	v_pk_mul_f32 v[0:1], v[4:5], v[0:1]
	v_lshlrev_b32_e32 v2, 16, v17
	v_cvt_pk_bf16_f32 v0, v0, v1
	v_mul_f32_e32 v1, 0xbfb8aa3b, v2
	v_exp_f32_e32 v1, v1
	v_and_b32_e32 v3, 0xffff0000, v17
	v_add_f32_e32 v1, 1.0, v1
	v_rcp_f32_e32 v4, v1
	v_mul_f32_e32 v1, 0xbfb8aa3b, v3
	v_exp_f32_e32 v1, v1
	s_nop 0
	v_add_f32_e32 v1, 1.0, v1
	v_rcp_f32_e32 v5, v1
	s_nop 0
	v_pk_mul_f32 v[2:3], v[4:5], v[2:3]
	s_nop 0
	v_pk_mul_f32 v[2:3], v[6:7], v[2:3]
	s_nop 0
	v_cvt_pk_bf16_f32 v1, v2, v3
	v_mov_b32_e32 v230, v0
	v_mov_b32_e32 v231, v1
	s_nop 1
	v_permlane32_swap_b32_e32 v228, v230
	v_permlane32_swap_b32_e32 v229, v231
	global_store_dwordx4 v[234:235], v[228:231], off offset:3168
	s_barrier
